# GEMM prologues: stage K-tile 0 and 1 back to back, RMS-stat partial sums deferred behind staging, lag barrier at loop entry
# baseline (speedup 1.0000x reference)
.LBB0_164:
	s_lshl_b32 s26, s8, 6
	v_ashrrev_i32_e32 v14, 6, v144
	s_lshl_b32 s8, s8, 13
	v_lshl_add_u32 v16, v14, 10, s8
	s_lshl_b32 s8, s88, 5
	s_and_b32 s20, s8, 0x60
	s_lshr_b32 s8, s20, 3
	v_add_lshl_u32 v14, v14, s8, 10
	s_mov_b64 s[8:9], 0x80
	s_add_i32 m0, s23, 0x18000
	v_lshl_add_u64 v[6:7], v[6:7], 0, s[8:9]
	global_load_lds_dwordx4 v[6:7], off
	v_lshl_add_u64 v[4:5], v[4:5], 0, s[8:9]
	s_add_i32 m0, s23, 0x1a000
	s_add_i32 s30, s23, 0x8000
	s_add_i32 s31, s23, 0xa000
	global_load_lds_dwordx4 v[4:5], off
	v_lshl_add_u64 v[2:3], v[2:3], 0, s[8:9]
	s_mov_b32 m0, s30
	s_add_u32 s16, s2, 0x80080
	global_load_lds_dwordx4 v[2:3], off
	v_lshl_add_u64 v[0:1], v[0:1], 0, s[8:9]
	s_mov_b32 m0, s31
	s_addc_u32 s17, s3, 0
	global_load_lds_dwordx4 v[0:1], off
	s_add_i32 m0, s23, 0x1c000
	v_lshl_add_u64 v[0:1], s[16:17], 0, v[130:131]
	global_load_lds_dwordx4 v[0:1], off
	v_lshl_add_u64 v[0:1], s[16:17], 0, v[134:135]
	s_add_i32 m0, s23, 0x1e000
	s_add_u32 s10, s94, s10
	global_load_lds_dwordx4 v[0:1], off
	v_lshlrev_b32_e32 v0, 15, v8
	v_and_b32_e32 v0, 0xffff0000, v0
	v_lshl_add_u32 v0, v9, 12, v0
	v_and_b32_e32 v1, 1, v8
	v_lshl_or_b32 v0, v1, 6, v0
	s_addc_u32 s11, s95, 0
	v_lshl_add_u32 v0, v10, 1, v0
	v_mov_b32_e32 v1, v131
	v_lshl_add_u64 v[0:1], s[10:11], 0, v[0:1]
	s_mov_b64 s[16:17], 0x11280080
	v_lshl_add_u64 v[136:137], v[0:1], 0, s[16:17]
	v_lshlrev_b32_e32 v0, 15, v11
	v_and_b32_e32 v0, 0xffff0000, v0
	v_lshl_add_u32 v0, v12, 12, v0
	v_and_b32_e32 v1, 1, v11
	v_lshl_or_b32 v0, v1, 6, v0
	v_lshl_add_u32 v0, v13, 1, v0
	v_mov_b32_e32 v1, v131
	v_lshl_add_u64 v[0:1], s[10:11], 0, v[0:1]
	v_lshl_add_u64 v[138:139], v[0:1], 0, s[16:17]
	s_lshl_b32 s15, s49, 18
	s_lshl_b32 s16, s62, 16
	s_and_b32 s15, s15, 0xe00000
	s_and_b32 s16, s16, 0x100000
	s_or_b32 s15, s15, s16
	s_add_u32 s12, s12, s15
	s_addc_u32 s13, s13, 0
	s_add_u32 s12, s94, s12
	v_and_b32_e32 v140, 15, v144
	v_and_b32_e32 v15, 48, v144
	v_lshlrev_b32_e32 v17, 2, v144
	s_addc_u32 s13, s95, s13
	v_lshl_or_b32 v15, v140, 6, v15
	v_and_b32_e32 v17, 32, v17
	s_add_u32 s34, s12, 0x4200100
	v_bitop3_b32 v14, v15, v14, v17 bitop3:0xde
	s_waitcnt vmcnt(6)
	s_addc_u32 s35, s13, 0
	s_add_i32 s39, 0, 0x10000
	s_add_i32 s41, 0, 0x14000
	s_add_i32 s43, 0, 0x18000
	s_add_i32 s45, 0, 0x1c000
	v_bitop3_b32 v16, v15, v16, v17 bitop3:0xde
	v_add_u32_e32 v141, s39, v14
	v_add_u32_e32 v142, s41, v14
	s_add_i32 s39, s39, s14
	s_add_i32 s41, s41, s14
	v_add_u32_e32 v145, s43, v14
	v_add_u32_e32 v146, s45, v14
	s_add_i32 s43, s43, s14
	s_add_i32 s45, s45, s14
	s_mov_b32 s36, -2
	s_mov_b64 s[12:13], 0
	v_add_u32_e32 v143, 0, v16
	s_add_i32 s37, s23, 0xc000
	s_add_i32 s38, s23, 0xe000
	s_add_i32 s40, s39, 0x2000
	s_add_i32 s42, s41, 0x2000
	s_add_i32 s44, s43, 0x2000
	s_add_i32 s46, s45, 0x2000
	v_mov_b32_e32 v0, v131
	v_mov_b32_e32 v1, v131
	v_mov_b32_e32 v2, v131
	v_mov_b32_e32 v3, v131
	v_mov_b32_e32 v4, v131
	v_mov_b32_e32 v5, v131
	v_mov_b32_e32 v6, v131
	v_mov_b32_e32 v7, v131
	v_mov_b32_e32 v16, v131
	v_mov_b32_e32 v17, v131
	v_mov_b32_e32 v18, v131
	v_mov_b32_e32 v19, v131
	v_mov_b32_e32 v20, v131
	v_mov_b32_e32 v21, v131
	v_mov_b32_e32 v22, v131
	v_mov_b32_e32 v23, v131
	v_mov_b32_e32 v32, v131
	v_mov_b32_e32 v33, v131
	v_mov_b32_e32 v34, v131
	v_mov_b32_e32 v35, v131
	v_mov_b32_e32 v36, v131
	v_mov_b32_e32 v37, v131
	v_mov_b32_e32 v38, v131
	v_mov_b32_e32 v39, v131
	v_mov_b32_e32 v48, v131
	v_mov_b32_e32 v49, v131
	v_mov_b32_e32 v50, v131
	v_mov_b32_e32 v51, v131
	v_mov_b32_e32 v52, v131
	v_mov_b32_e32 v53, v131
	v_mov_b32_e32 v54, v131
	v_mov_b32_e32 v55, v131
	v_mov_b32_e32 v8, v131
	v_mov_b32_e32 v9, v131
	v_mov_b32_e32 v10, v131
	v_mov_b32_e32 v11, v131
	v_mov_b32_e32 v12, v131
	v_mov_b32_e32 v13, v131
	v_mov_b32_e32 v14, v131
	v_mov_b32_e32 v15, v131
	v_mov_b32_e32 v24, v131
	v_mov_b32_e32 v25, v131
	v_mov_b32_e32 v26, v131
	v_mov_b32_e32 v27, v131
	v_mov_b32_e32 v28, v131
	v_mov_b32_e32 v29, v131
	v_mov_b32_e32 v30, v131
	v_mov_b32_e32 v31, v131
	v_mov_b32_e32 v40, v131
	v_mov_b32_e32 v41, v131
	v_mov_b32_e32 v42, v131
	v_mov_b32_e32 v43, v131
	v_mov_b32_e32 v44, v131
	v_mov_b32_e32 v45, v131
	v_mov_b32_e32 v46, v131
	v_mov_b32_e32 v47, v131
	v_mov_b32_e32 v56, v131
	v_mov_b32_e32 v57, v131
	v_mov_b32_e32 v58, v131
	v_mov_b32_e32 v59, v131
	v_mov_b32_e32 v60, v131
	v_mov_b32_e32 v61, v131
	v_mov_b32_e32 v62, v131
	v_mov_b32_e32 v63, v131
	v_mov_b32_e32 v64, v131
	v_mov_b32_e32 v65, v131
	v_mov_b32_e32 v66, v131
	v_mov_b32_e32 v67, v131
	v_mov_b32_e32 v68, v131
	v_mov_b32_e32 v69, v131
	v_mov_b32_e32 v70, v131
	v_mov_b32_e32 v71, v131
	v_mov_b32_e32 v80, v131
	v_mov_b32_e32 v81, v131
	v_mov_b32_e32 v82, v131
	v_mov_b32_e32 v83, v131
	v_mov_b32_e32 v84, v131
	v_mov_b32_e32 v85, v131
	v_mov_b32_e32 v86, v131
	v_mov_b32_e32 v87, v131
	v_mov_b32_e32 v96, v131
	v_mov_b32_e32 v97, v131
	v_mov_b32_e32 v98, v131
	v_mov_b32_e32 v99, v131
	v_mov_b32_e32 v100, v131
	v_mov_b32_e32 v101, v131
	v_mov_b32_e32 v102, v131
	v_mov_b32_e32 v103, v131
	v_mov_b32_e32 v112, v131
	v_mov_b32_e32 v113, v131
	v_mov_b32_e32 v114, v131
	v_mov_b32_e32 v115, v131
	v_mov_b32_e32 v116, v131
	v_mov_b32_e32 v117, v131
	v_mov_b32_e32 v118, v131
	v_mov_b32_e32 v119, v131
	v_mov_b32_e32 v72, v131
	v_mov_b32_e32 v73, v131
	v_mov_b32_e32 v74, v131
	v_mov_b32_e32 v75, v131
	v_mov_b32_e32 v76, v131
	v_mov_b32_e32 v77, v131
	v_mov_b32_e32 v78, v131
	v_mov_b32_e32 v79, v131
	v_mov_b32_e32 v88, v131
	v_mov_b32_e32 v89, v131
	v_mov_b32_e32 v90, v131
	v_mov_b32_e32 v91, v131
	v_mov_b32_e32 v92, v131
	v_mov_b32_e32 v93, v131
	v_mov_b32_e32 v94, v131
	v_mov_b32_e32 v95, v131
	v_mov_b32_e32 v104, v131
	v_mov_b32_e32 v105, v131
	v_mov_b32_e32 v106, v131
	v_mov_b32_e32 v107, v131
	v_mov_b32_e32 v108, v131
	v_mov_b32_e32 v109, v131
	v_mov_b32_e32 v110, v131
	v_mov_b32_e32 v111, v131
	v_mov_b32_e32 v120, v131
	v_mov_b32_e32 v121, v131
	v_mov_b32_e32 v122, v131
	v_mov_b32_e32 v123, v131
	v_mov_b32_e32 v124, v131
	v_mov_b32_e32 v125, v131
	v_mov_b32_e32 v126, v131
	v_mov_b32_e32 v127, v131
	s_barrier
	s_lshr_b32 s100, s88, 2
	s_cmp_lg_u32 s100, 1
	s_cbranch_scc1 .Lpro_lag0
	s_barrier
.Lpro_lag0:
.LBB0_165:
	ds_read_b128 v[148:151], v141
	ds_read_b128 v[152:155], v141 offset:1024
	ds_read_b128 v[156:159], v141 offset:2048
	ds_read_b128 v[160:163], v141 offset:3072
	ds_read_b128 v[164:167], v142
	ds_read_b128 v[168:171], v142 offset:1024
	ds_read_b128 v[172:175], v142 offset:2048
	ds_read_b128 v[176:179], v142 offset:3072
	s_add_u32 s14, s10, s12
	s_addc_u32 s15, s11, s13
	s_add_u32 s14, s14, 0x11200100
	s_addc_u32 s15, s15, 0
	s_add_u32 s47, s34, s12
	s_addc_u32 s50, s35, s13
	s_cmpk_eq_i32 s12, 0xf00
	s_cselect_b32 s17, s7, s15
	s_cselect_b32 s16, s6, s14
	s_cselect_b32 s15, s3, s50
	s_cselect_b32 s14, s2, s47
	s_mov_b32 m0, s37
	v_lshl_add_u64 v[212:213], v[136:137], 0, s[12:13]
	ds_read_b128 v[180:183], v143
	ds_read_b128 v[184:187], v143 offset:1024
	ds_read_b128 v[188:191], v143 offset:2048
	ds_read_b128 v[192:195], v143 offset:3072
	ds_read_b128 v[196:199], v143 offset:4096
	ds_read_b128 v[200:203], v143 offset:5120
	ds_read_b128 v[204:207], v143 offset:6144
	ds_read_b128 v[208:211], v143 offset:7168
	global_load_lds_dwordx4 v[212:213], off
	v_lshl_add_u64 v[212:213], v[138:139], 0, s[12:13]
	s_mov_b32 m0, s38
	s_nop 0
	global_load_lds_dwordx4 v[212:213], off
	s_waitcnt vmcnt(8)
	s_waitcnt lgkmcnt(0)
	s_barrier
	s_setprio 1
	s_waitcnt lgkmcnt(0)
	v_mfma_f32_16x16x32_bf16 v[124:127], v[148:151], v[180:183], v[124:127]
	v_mfma_f32_16x16x32_bf16 v[120:123], v[156:159], v[180:183], v[120:123]
	v_mfma_f32_16x16x32_bf16 v[108:111], v[148:151], v[188:191], v[108:111]
	v_mfma_f32_16x16x32_bf16 v[104:107], v[156:159], v[188:191], v[104:107]
	v_mfma_f32_16x16x32_bf16 v[92:95], v[148:151], v[196:199], v[92:95]
	v_mfma_f32_16x16x32_bf16 v[88:91], v[156:159], v[196:199], v[88:91]
	v_mfma_f32_16x16x32_bf16 v[76:79], v[148:151], v[204:207], v[76:79]
	v_mfma_f32_16x16x32_bf16 v[72:75], v[156:159], v[204:207], v[72:75]
	v_mfma_f32_16x16x32_bf16 v[124:127], v[152:155], v[184:187], v[124:127]
	v_mfma_f32_16x16x32_bf16 v[120:123], v[160:163], v[184:187], v[120:123]
	v_mfma_f32_16x16x32_bf16 v[108:111], v[152:155], v[192:195], v[108:111]
	v_mfma_f32_16x16x32_bf16 v[104:107], v[160:163], v[192:195], v[104:107]
	v_mfma_f32_16x16x32_bf16 v[92:95], v[152:155], v[200:203], v[92:95]
	v_mfma_f32_16x16x32_bf16 v[88:91], v[160:163], v[200:203], v[88:91]
	v_mfma_f32_16x16x32_bf16 v[76:79], v[152:155], v[208:211], v[76:79]
	v_mfma_f32_16x16x32_bf16 v[72:75], v[160:163], v[208:211], v[72:75]
	s_setprio 0
	s_setprio 1
	v_mfma_f32_16x16x32_bf16 v[116:119], v[164:167], v[180:183], v[116:119]
	v_mfma_f32_16x16x32_bf16 v[112:115], v[172:175], v[180:183], v[112:115]
	v_mfma_f32_16x16x32_bf16 v[100:103], v[164:167], v[188:191], v[100:103]
	v_mfma_f32_16x16x32_bf16 v[96:99], v[172:175], v[188:191], v[96:99]
	v_mfma_f32_16x16x32_bf16 v[84:87], v[164:167], v[196:199], v[84:87]
	v_mfma_f32_16x16x32_bf16 v[80:83], v[172:175], v[196:199], v[80:83]
	v_mfma_f32_16x16x32_bf16 v[68:71], v[164:167], v[204:207], v[68:71]
	v_mfma_f32_16x16x32_bf16 v[64:67], v[172:175], v[204:207], v[64:67]
	v_mfma_f32_16x16x32_bf16 v[116:119], v[168:171], v[184:187], v[116:119]
	v_mfma_f32_16x16x32_bf16 v[112:115], v[176:179], v[184:187], v[112:115]
	v_mfma_f32_16x16x32_bf16 v[100:103], v[168:171], v[192:195], v[100:103]
	v_mfma_f32_16x16x32_bf16 v[96:99], v[176:179], v[192:195], v[96:99]
	v_mfma_f32_16x16x32_bf16 v[84:87], v[168:171], v[200:203], v[84:87]
	v_mfma_f32_16x16x32_bf16 v[80:83], v[176:179], v[200:203], v[80:83]
	v_mfma_f32_16x16x32_bf16 v[68:71], v[168:171], v[208:211], v[68:71]
	v_mfma_f32_16x16x32_bf16 v[64:67], v[176:179], v[208:211], v[64:67]
	s_setprio 0
	s_barrier
	s_mov_b32 m0, s39
	v_lshl_add_u64 v[212:213], s[14:15], 0, v[130:131]
	s_add_u32 s50, s14, 0x80000
	ds_read_b128 v[180:183], v143 offset:16384
	ds_read_b128 v[184:187], v143 offset:17408
	ds_read_b128 v[188:191], v143 offset:18432
	ds_read_b128 v[192:195], v143 offset:19456
	ds_read_b128 v[196:199], v143 offset:20480
	ds_read_b128 v[200:203], v143 offset:21504
	ds_read_b128 v[204:207], v143 offset:22528
	ds_read_b128 v[208:211], v143 offset:23552
	global_load_lds_dwordx4 v[212:213], off
	v_lshl_add_u64 v[214:215], s[14:15], 0, v[134:135]
	s_mov_b32 m0, s40
	s_addc_u32 s51, s15, 0
	global_load_lds_dwordx4 v[214:215], off
	v_lshl_add_u64 v[216:217], s[50:51], 0, v[130:131]
	s_mov_b32 m0, s41
	v_lshl_add_u64 v[218:219], s[16:17], 0, v[132:133]
	global_load_lds_dwordx4 v[216:217], off
	v_lshl_add_u64 v[216:217], s[50:51], 0, v[134:135]
	s_mov_b32 m0, s42
	s_nop 0
	global_load_lds_dwordx4 v[216:217], off
	v_lshl_add_u64 v[216:217], s[16:17], 0, v[128:129]
	s_mov_b32 m0, s23
	s_nop 0
	global_load_lds_dwordx4 v[216:217], off
	s_mov_b32 m0, s27
	s_nop 0
	global_load_lds_dwordx4 v[218:219], off
	s_waitcnt vmcnt(8)
	s_waitcnt lgkmcnt(0)
	s_barrier
	s_setprio 1
	s_waitcnt lgkmcnt(0)
	v_mfma_f32_16x16x32_bf16 v[60:63], v[148:151], v[180:183], v[60:63]
	v_mfma_f32_16x16x32_bf16 v[56:59], v[156:159], v[180:183], v[56:59]
	v_mfma_f32_16x16x32_bf16 v[44:47], v[148:151], v[188:191], v[44:47]
	v_mfma_f32_16x16x32_bf16 v[40:43], v[156:159], v[188:191], v[40:43]
	v_mfma_f32_16x16x32_bf16 v[28:31], v[148:151], v[196:199], v[28:31]
	v_mfma_f32_16x16x32_bf16 v[24:27], v[156:159], v[196:199], v[24:27]
	v_mfma_f32_16x16x32_bf16 v[12:15], v[148:151], v[204:207], v[12:15]
	v_mfma_f32_16x16x32_bf16 v[8:11], v[156:159], v[204:207], v[8:11]
	v_mfma_f32_16x16x32_bf16 v[60:63], v[152:155], v[184:187], v[60:63]
	v_mfma_f32_16x16x32_bf16 v[56:59], v[160:163], v[184:187], v[56:59]
	v_mfma_f32_16x16x32_bf16 v[44:47], v[152:155], v[192:195], v[44:47]
	v_mfma_f32_16x16x32_bf16 v[40:43], v[160:163], v[192:195], v[40:43]
	v_mfma_f32_16x16x32_bf16 v[28:31], v[152:155], v[200:203], v[28:31]
	v_mfma_f32_16x16x32_bf16 v[24:27], v[160:163], v[200:203], v[24:27]
	v_mfma_f32_16x16x32_bf16 v[12:15], v[152:155], v[208:211], v[12:15]
	v_mfma_f32_16x16x32_bf16 v[8:11], v[160:163], v[208:211], v[8:11]
	s_setprio 0
	s_setprio 1
	v_mfma_f32_16x16x32_bf16 v[52:55], v[164:167], v[180:183], v[52:55]
	v_mfma_f32_16x16x32_bf16 v[48:51], v[172:175], v[180:183], v[48:51]
	v_mfma_f32_16x16x32_bf16 v[36:39], v[164:167], v[188:191], v[36:39]
	v_mfma_f32_16x16x32_bf16 v[32:35], v[172:175], v[188:191], v[32:35]
	v_mfma_f32_16x16x32_bf16 v[20:23], v[164:167], v[196:199], v[20:23]
	v_mfma_f32_16x16x32_bf16 v[16:19], v[172:175], v[196:199], v[16:19]
	v_mfma_f32_16x16x32_bf16 v[4:7], v[164:167], v[204:207], v[4:7]
	v_mfma_f32_16x16x32_bf16 v[0:3], v[172:175], v[204:207], v[0:3]
	v_mfma_f32_16x16x32_bf16 v[52:55], v[168:171], v[184:187], v[52:55]
	v_mfma_f32_16x16x32_bf16 v[48:51], v[176:179], v[184:187], v[48:51]
	v_mfma_f32_16x16x32_bf16 v[36:39], v[168:171], v[192:195], v[36:39]
	v_mfma_f32_16x16x32_bf16 v[32:35], v[176:179], v[192:195], v[32:35]
	v_mfma_f32_16x16x32_bf16 v[20:23], v[168:171], v[200:203], v[20:23]
	v_mfma_f32_16x16x32_bf16 v[16:19], v[176:179], v[200:203], v[16:19]
	v_mfma_f32_16x16x32_bf16 v[4:7], v[168:171], v[208:211], v[4:7]
	v_mfma_f32_16x16x32_bf16 v[0:3], v[176:179], v[208:211], v[0:3]
	s_setprio 0
	s_barrier
	ds_read_b128 v[148:151], v145
	ds_read_b128 v[152:155], v145 offset:1024
	ds_read_b128 v[156:159], v145 offset:2048
	ds_read_b128 v[160:163], v145 offset:3072
	ds_read_b128 v[164:167], v146
	ds_read_b128 v[168:171], v146 offset:1024
	ds_read_b128 v[172:175], v146 offset:2048
	ds_read_b128 v[176:179], v146 offset:3072
	s_add_u32 s16, s16, 0x80000
	s_addc_u32 s17, s17, 0
	s_mov_b32 m0, s28
	v_lshl_add_u64 v[220:221], s[16:17], 0, v[128:129]
	ds_read_b128 v[180:183], v143 offset:32768
	ds_read_b128 v[184:187], v143 offset:33792
	ds_read_b128 v[188:191], v143 offset:34816
	ds_read_b128 v[192:195], v143 offset:35840
	ds_read_b128 v[196:199], v143 offset:36864
	ds_read_b128 v[200:203], v143 offset:37888
	ds_read_b128 v[204:207], v143 offset:38912
	ds_read_b128 v[208:211], v143 offset:39936
	global_load_lds_dwordx4 v[220:221], off
	v_lshl_add_u64 v[220:221], s[16:17], 0, v[132:133]
	s_mov_b32 m0, s29
	s_nop 0
	global_load_lds_dwordx4 v[220:221], off
	s_waitcnt vmcnt(8)
	s_waitcnt lgkmcnt(0)
	s_barrier
	s_setprio 1
	s_waitcnt lgkmcnt(0)
	v_mfma_f32_16x16x32_bf16 v[124:127], v[148:151], v[180:183], v[124:127]
	v_mfma_f32_16x16x32_bf16 v[120:123], v[156:159], v[180:183], v[120:123]
	v_mfma_f32_16x16x32_bf16 v[108:111], v[148:151], v[188:191], v[108:111]
	v_mfma_f32_16x16x32_bf16 v[104:107], v[156:159], v[188:191], v[104:107]
	v_mfma_f32_16x16x32_bf16 v[92:95], v[148:151], v[196:199], v[92:95]
	v_mfma_f32_16x16x32_bf16 v[88:91], v[156:159], v[196:199], v[88:91]
	v_mfma_f32_16x16x32_bf16 v[76:79], v[148:151], v[204:207], v[76:79]
	v_mfma_f32_16x16x32_bf16 v[72:75], v[156:159], v[204:207], v[72:75]
	v_mfma_f32_16x16x32_bf16 v[124:127], v[152:155], v[184:187], v[124:127]
	v_mfma_f32_16x16x32_bf16 v[120:123], v[160:163], v[184:187], v[120:123]
	v_mfma_f32_16x16x32_bf16 v[108:111], v[152:155], v[192:195], v[108:111]
	v_mfma_f32_16x16x32_bf16 v[104:107], v[160:163], v[192:195], v[104:107]
	v_mfma_f32_16x16x32_bf16 v[92:95], v[152:155], v[200:203], v[92:95]
	v_mfma_f32_16x16x32_bf16 v[88:91], v[160:163], v[200:203], v[88:91]
	v_mfma_f32_16x16x32_bf16 v[76:79], v[152:155], v[208:211], v[76:79]
	v_mfma_f32_16x16x32_bf16 v[72:75], v[160:163], v[208:211], v[72:75]
	s_setprio 0
	s_setprio 1
	v_mfma_f32_16x16x32_bf16 v[116:119], v[164:167], v[180:183], v[116:119]
	v_mfma_f32_16x16x32_bf16 v[112:115], v[172:175], v[180:183], v[112:115]
	v_mfma_f32_16x16x32_bf16 v[100:103], v[164:167], v[188:191], v[100:103]
	v_mfma_f32_16x16x32_bf16 v[96:99], v[172:175], v[188:191], v[96:99]
	v_mfma_f32_16x16x32_bf16 v[84:87], v[164:167], v[196:199], v[84:87]
	v_mfma_f32_16x16x32_bf16 v[80:83], v[172:175], v[196:199], v[80:83]
	v_mfma_f32_16x16x32_bf16 v[68:71], v[164:167], v[204:207], v[68:71]
	v_mfma_f32_16x16x32_bf16 v[64:67], v[172:175], v[204:207], v[64:67]
	v_mfma_f32_16x16x32_bf16 v[116:119], v[168:171], v[184:187], v[116:119]
	v_mfma_f32_16x16x32_bf16 v[112:115], v[176:179], v[184:187], v[112:115]
	v_mfma_f32_16x16x32_bf16 v[100:103], v[168:171], v[192:195], v[100:103]
	v_mfma_f32_16x16x32_bf16 v[96:99], v[176:179], v[192:195], v[96:99]
	v_mfma_f32_16x16x32_bf16 v[84:87], v[168:171], v[200:203], v[84:87]
	v_mfma_f32_16x16x32_bf16 v[80:83], v[176:179], v[200:203], v[80:83]
	v_mfma_f32_16x16x32_bf16 v[68:71], v[168:171], v[208:211], v[68:71]
	v_mfma_f32_16x16x32_bf16 v[64:67], v[176:179], v[208:211], v[64:67]
	s_setprio 0
	s_barrier
	s_mov_b32 m0, s43
	v_lshl_add_u64 v[212:213], v[212:213], 0, s[8:9]
	s_add_u32 s14, s14, 0x80080
	ds_read_b128 v[180:183], v143 offset:49152
	ds_read_b128 v[184:187], v143 offset:50176
	ds_read_b128 v[188:191], v143 offset:51200
	ds_read_b128 v[192:195], v143 offset:52224
	ds_read_b128 v[196:199], v143 offset:53248
	ds_read_b128 v[200:203], v143 offset:54272
	ds_read_b128 v[204:207], v143 offset:55296
	ds_read_b128 v[208:211], v143 offset:56320
	global_load_lds_dwordx4 v[212:213], off
	v_lshl_add_u64 v[212:213], v[214:215], 0, s[8:9]
	s_mov_b32 m0, s44
	s_addc_u32 s15, s15, 0
	global_load_lds_dwordx4 v[212:213], off
	v_lshl_add_u64 v[212:213], s[14:15], 0, v[130:131]
	s_mov_b32 m0, s45
	s_nop 0
	global_load_lds_dwordx4 v[212:213], off
	v_lshl_add_u64 v[212:213], s[14:15], 0, v[134:135]
	s_mov_b32 m0, s46
	s_nop 0
	global_load_lds_dwordx4 v[212:213], off
	v_lshl_add_u64 v[212:213], v[216:217], 0, s[8:9]
	s_mov_b32 m0, s30
	s_nop 0
	global_load_lds_dwordx4 v[212:213], off
	v_lshl_add_u64 v[212:213], v[218:219], 0, s[8:9]
	s_mov_b32 m0, s31
	s_nop 0
	global_load_lds_dwordx4 v[212:213], off
	s_waitcnt vmcnt(8)
	s_waitcnt lgkmcnt(0)
	s_barrier
	s_setprio 1
	s_waitcnt lgkmcnt(0)
	v_mfma_f32_16x16x32_bf16 v[60:63], v[148:151], v[180:183], v[60:63]
	v_mfma_f32_16x16x32_bf16 v[56:59], v[156:159], v[180:183], v[56:59]
	v_mfma_f32_16x16x32_bf16 v[44:47], v[148:151], v[188:191], v[44:47]
	v_mfma_f32_16x16x32_bf16 v[40:43], v[156:159], v[188:191], v[40:43]
	v_mfma_f32_16x16x32_bf16 v[28:31], v[148:151], v[196:199], v[28:31]
	v_mfma_f32_16x16x32_bf16 v[24:27], v[156:159], v[196:199], v[24:27]
	v_mfma_f32_16x16x32_bf16 v[12:15], v[148:151], v[204:207], v[12:15]
	v_mfma_f32_16x16x32_bf16 v[8:11], v[156:159], v[204:207], v[8:11]
	v_mfma_f32_16x16x32_bf16 v[60:63], v[152:155], v[184:187], v[60:63]
	v_mfma_f32_16x16x32_bf16 v[56:59], v[160:163], v[184:187], v[56:59]
	v_mfma_f32_16x16x32_bf16 v[44:47], v[152:155], v[192:195], v[44:47]
	v_mfma_f32_16x16x32_bf16 v[40:43], v[160:163], v[192:195], v[40:43]
	v_mfma_f32_16x16x32_bf16 v[28:31], v[152:155], v[200:203], v[28:31]
	v_mfma_f32_16x16x32_bf16 v[24:27], v[160:163], v[200:203], v[24:27]
	v_mfma_f32_16x16x32_bf16 v[12:15], v[152:155], v[208:211], v[12:15]
	v_mfma_f32_16x16x32_bf16 v[8:11], v[160:163], v[208:211], v[8:11]
	s_setprio 0
	s_setprio 1
	v_mfma_f32_16x16x32_bf16 v[52:55], v[164:167], v[180:183], v[52:55]
	v_mfma_f32_16x16x32_bf16 v[48:51], v[172:175], v[180:183], v[48:51]
	v_mfma_f32_16x16x32_bf16 v[36:39], v[164:167], v[188:191], v[36:39]
	v_mfma_f32_16x16x32_bf16 v[32:35], v[172:175], v[188:191], v[32:35]
	v_mfma_f32_16x16x32_bf16 v[20:23], v[164:167], v[196:199], v[20:23]
	v_mfma_f32_16x16x32_bf16 v[16:19], v[172:175], v[196:199], v[16:19]
	v_mfma_f32_16x16x32_bf16 v[4:7], v[164:167], v[204:207], v[4:7]
	v_mfma_f32_16x16x32_bf16 v[0:3], v[172:175], v[204:207], v[0:3]
	v_mfma_f32_16x16x32_bf16 v[52:55], v[168:171], v[184:187], v[52:55]
	v_mfma_f32_16x16x32_bf16 v[48:51], v[176:179], v[184:187], v[48:51]
	v_mfma_f32_16x16x32_bf16 v[36:39], v[168:171], v[192:195], v[36:39]
	v_mfma_f32_16x16x32_bf16 v[32:35], v[176:179], v[192:195], v[32:35]
	v_mfma_f32_16x16x32_bf16 v[20:23], v[168:171], v[200:203], v[20:23]
	v_mfma_f32_16x16x32_bf16 v[16:19], v[176:179], v[200:203], v[16:19]
	v_mfma_f32_16x16x32_bf16 v[4:7], v[168:171], v[208:211], v[4:7]
	v_mfma_f32_16x16x32_bf16 v[0:3], v[176:179], v[208:211], v[0:3]
	s_setprio 0
	s_barrier
	s_add_i32 s36, s36, 2
	s_add_u32 s12, s12, 0x100
	s_addc_u32 s13, s13, 0
	s_cmp_gt_u32 s36, 29
	s_cbranch_scc0 .LBB0_165
	s_cmpk_lt_u32 s33, 0x100
	s_cbranch_scc0 .LBB0_168
	s_barrier

.LBB0_242:
	s_add_u32 s21, s94, 0xf200000
	s_addc_u32 s23, s95, 0
	s_add_u32 s4, s94, 0x12000000
	s_addc_u32 s5, s95, 0
	s_mul_i32 s0, s64, 0x1400000
	s_add_u32 s0, s94, s0
	s_addc_u32 s1, s95, 0
	s_lshl_b32 s2, s64, 23
	s_sub_u32 s2, 0, s2
	s_subb_u32 s3, 0, 0
	s_add_u32 s0, s0, s2
	s_addc_u32 s1, s1, s3
	s_add_u32 s28, s0, 0x13000000
	s_addc_u32 s29, s1, 0
	s_add_u32 s70, s94, 0x200000
	s_addc_u32 s71, s95, 0
	s_add_u32 s26, s94, 0x12200000
	s_addc_u32 s27, s95, 0
	s_and_b32 s67, s33, 0xffffffc0
	v_add_u32_e32 v146, s67, v144
	v_ashrrev_i32_e32 v147, 31, v146
	s_waitcnt vmcnt(1)
	v_lshrrev_b32_e32 v1, 26, v147
	v_add_u32_e32 v1, v146, v1
	v_ashrrev_i32_e32 v186, 6, v1
	v_bfe_i32 v1, v146, 27, 1
	v_lshlrev_b32_e32 v0, 4, v146
	v_lshrrev_b32_e32 v1, 22, v1
	v_add_u32_e32 v1, v0, v1
	v_and_b32_e32 v1, 0xfffffc00, v1
	v_sub_u32_e32 v1, v0, v1
	v_lshrrev_b32_e32 v2, 4, v1
	v_bitop3_b32 v1, v2, v1, 32 bitop3:0x6c
	v_ashrrev_i32_e32 v3, 31, v1
	v_lshrrev_b32_e32 v3, 26, v3
	v_add_u32_e32 v3, v1, v3
	v_lshlrev_b32_e32 v2, 3, v186
	v_ashrrev_i32_e32 v187, 6, v3
	v_and_b32_e32 v3, 0xc0, v3
	s_mov_b64 s[0:1], s[90:91]
	v_and_b32_e32 v2, -16, v2
	v_sub_u32_e32 v1, v1, v3
	v_mov_b32_e32 v3, 1
	v_add_u32_e32 v2, v187, v2
	v_ashrrev_i16_sdwa v1, v3, sext(v1) dst_sel:DWORD dst_unused:UNUSED_PAD src0_sel:DWORD src1_sel:BYTE_0
	s_load_dwordx2 s[30:31], s[0:1], 0x40
	s_waitcnt vmcnt(0)
	v_lshlrev_b32_e32 v4, 5, v186
	v_bfe_i32 v188, v1, 0, 16
	v_lshlrev_b32_e32 v1, 1, v2
	v_lshrrev_b32_e32 v5, 2, v2
	v_and_b32_e32 v6, 3, v187
	s_mov_b32 s0, 0xfffe0
	v_and_b32_e32 v4, 32, v4
	v_and_b32_e32 v1, 24, v1
	v_and_b32_e32 v5, 4, v5
	v_and_or_b32 v6, v2, s0, v6
	v_or3_b32 v1, v6, v5, v1
	v_add_lshl_u32 v4, v4, v188, 1
	v_add_u32_e32 v0, 0x2000, v0
	v_lshl_add_u32 v150, v1, 12, v4
	v_ashrrev_i32_e32 v1, 31, v0
	v_lshrrev_b32_e32 v1, 22, v1
	v_add_u32_e32 v1, v0, v1
	v_ashrrev_i32_e32 v189, 10, v1
	v_mul_i32_i24_e32 v1, 0x400, v189
	v_sub_u32_e32 v0, v0, v1
	v_lshrrev_b32_e32 v1, 4, v0
	v_bitop3_b32 v0, v1, v0, 32 bitop3:0x6c
	v_lshl_add_u32 v148, v2, 12, v4
	v_ashrrev_i32_e32 v2, 31, v0
	v_lshrrev_b32_e32 v2, 26, v2
	v_add_u32_e32 v2, v0, v2
	v_lshlrev_b32_e32 v1, 3, v189
	v_ashrrev_i32_e32 v190, 6, v2
	v_and_b32_e32 v2, 0xc0, v2
	v_and_b32_e32 v1, -16, v1
	v_sub_u32_e32 v0, v0, v2
	v_add_u32_e32 v1, v190, v1
	v_ashrrev_i16_sdwa v0, v3, sext(v0) dst_sel:DWORD dst_unused:UNUSED_PAD src0_sel:DWORD src1_sel:BYTE_0
	v_lshlrev_b32_e32 v4, 5, v189
	v_bfe_i32 v191, v0, 0, 16
	v_lshlrev_b32_e32 v0, 1, v1
	v_lshrrev_b32_e32 v2, 2, v1
	v_and_b32_e32 v3, 3, v190
	v_and_b32_e32 v4, 32, v4
	v_and_b32_e32 v0, 24, v0
	v_and_b32_e32 v2, 4, v2
	v_and_or_b32 v3, v1, s0, v3
	v_or3_b32 v0, v3, v2, v0
	v_add_lshl_u32 v2, v4, v191, 1
	v_lshl_add_u32 v152, v1, 12, v2
	v_lshlrev_b32_e32 v1, 4, v144
	s_lshr_b32 s37, s33, 8
	v_and_b32_e32 v145, 15, v144
	v_lshl_add_u32 v154, v0, 12, v2
	s_bfe_u32 s43, s33, 0x20006
	v_and_b32_e32 v0, 48, v144
	v_and_b32_e32 v1, 0xfffffc00, v1
	v_lshlrev_b32_e32 v185, 2, v144
	v_lshl_add_u32 v2, s37, 13, v1
	v_lshl_or_b32 v0, v145, 6, v0
	v_and_b32_e32 v3, 32, v185
	v_lshl_add_u32 v1, s43, 12, v1
	v_ashrrev_i32_e32 v184, 4, v144
	s_lshl_b32 s66, s88, 10
	s_lshl_b32 s68, s37, 6
	v_bitop3_b32 v193, v0, v2, v3 bitop3:0xde
	s_lshl_b32 s69, s43, 5
	v_bitop3_b32 v192, v0, v1, v3 bitop3:0xde
	s_mov_b64 s[0:1], -1
	s_and_b64 vcc, exec, s[34:35]
	s_cbranch_vccz .LBB0_286
	s_cmp_gt_i32 s63, 63
	s_cbranch_scc1 .LBB0_285
	s_bfe_u32 s0, s49, 0x20003
	s_lshl_b32 s1, s64, 2
	s_or_b32 s35, s1, s0
	s_movk_i32 s0, 0x100
	v_cmp_gt_i32_e32 vcc, s0, v146
	s_and_saveexec_b64 s[0:1], vcc
	s_cbranch_execz .LBB0_246
	v_lshl_add_u32 v0, s35, 8, v146
	v_ashrrev_i32_e32 v1, 31, v0
	v_lshlrev_b64 v[0:1], 8, v[0:1]
	v_lshl_add_u64 v[8:9], s[4:5], 0, v[0:1]
	global_load_dwordx4 v[248:251], v[8:9], off offset:64
	global_load_dwordx4 v[244:247], v[8:9], off
	global_load_dwordx4 v[240:243], v[8:9], off offset:16
	global_load_dwordx4 v[236:239], v[8:9], off offset:80
	global_load_dwordx4 v[232:235], v[8:9], off offset:96
	global_load_dwordx4 v[228:231], v[8:9], off offset:32
	global_load_dwordx4 v[224:227], v[8:9], off offset:48
	global_load_dwordx4 v[220:223], v[8:9], off offset:112

.LBB0_248:
	s_mov_b64 s[14:15], 0x80
	s_add_i32 m0, s7, 0x18000
	v_lshl_add_u64 v[22:23], v[22:23], 0, s[14:15]
	global_load_lds_dwordx4 v[22:23], off
	v_lshl_add_u64 v[20:21], v[20:21], 0, s[14:15]
	s_add_i32 m0, s7, 0x1a000
	s_add_i32 s51, s7, 0x8000
	s_add_i32 s52, s7, 0xa000
	global_load_lds_dwordx4 v[20:21], off
	v_lshl_add_u64 v[16:17], v[16:17], 0, s[14:15]
	s_mov_b32 m0, s51
	s_add_u32 s0, s10, 0x80080
	global_load_lds_dwordx4 v[16:17], off
	v_lshl_add_u64 v[16:17], v[18:19], 0, s[14:15]
	s_mov_b32 m0, s52
	s_addc_u32 s1, s11, 0
	global_load_lds_dwordx4 v[16:17], off
	s_add_i32 m0, s7, 0x1c000
	v_lshl_add_u64 v[16:17], s[0:1], 0, v[150:151]
	global_load_lds_dwordx4 v[16:17], off
	v_lshl_add_u64 v[16:17], s[0:1], 0, v[154:155]
	s_add_i32 m0, s7, 0x1e000
	s_nop 0
	global_load_lds_dwordx4 v[16:17], off
	s_waitcnt vmcnt(6)
	s_barrier
	s_and_saveexec_b64 s[0:1], vcc
	s_cbranch_execz .LBB0_250
	v_pk_add_f32 v[8:9], v[246:247], v[250:251]
	v_pk_add_f32 v[12:13], v[244:245], v[248:249]
	v_pk_add_f32 v[10:11], v[242:243], v[238:239]
	v_pk_add_f32 v[14:15], v[240:241], v[236:237]
	v_pk_add_f32 v[0:1], v[230:231], v[234:235]
	v_pk_add_f32 v[4:5], v[228:229], v[232:233]
	v_pk_add_f32 v[2:3], v[226:227], v[222:223]
	v_pk_add_f32 v[6:7], v[224:225], v[220:221]
	v_pk_add_f32 v[12:13], v[14:15], v[12:13]
	v_pk_add_f32 v[8:9], v[10:11], v[8:9]
	v_pk_add_f32 v[4:5], v[6:7], v[4:5]
	v_pk_add_f32 v[0:1], v[2:3], v[0:1]
	v_pk_add_f32 v[2:3], v[4:5], v[12:13]
	v_pk_add_f32 v[0:1], v[0:1], v[8:9]
	s_nop 0
	v_pk_mov_b32 v[4:5], v[2:3], v[0:1] op_sel:[1,0]
	v_mov_b32_e32 v3, v1
	v_pk_add_f32 v[0:1], v[4:5], v[2:3]
	s_nop 0
	v_add_f32_e32 v0, v0, v1
	v_mov_b32_e32 v1, 0x358637bd
	v_fmac_f32_e32 v1, 0x3a000000, v0
	v_rsq_f32_e32 v0, v1
	v_lshl_add_u32 v1, v146, 2, 0
	v_add_u32_e32 v1, 0x20000, v1
	ds_write_b32 v1, v0
.LBB0_250:
	s_or_b64 exec, exec, s[0:1]
	v_lshlrev_b32_e32 v0, 15, v186
	v_and_b32_e32 v0, 0xffff0000, v0
	v_lshl_add_u32 v0, v187, 12, v0
	v_and_b32_e32 v1, 1, v186
	s_cmpk_lt_u32 s33, 0x100
	v_lshl_or_b32 v0, v1, 6, v0
	s_cselect_b64 s[16:17], -1, 0
	s_lshl_b32 s53, s43, 1
	v_lshl_add_u32 v156, v188, 1, v0
	v_lshlrev_b32_e32 v0, 15, v189
	s_orn2_b32 s53, s53, 63
	v_and_b32_e32 v0, 0xffff0000, v0
	s_waitcnt lgkmcnt(0)
	s_cmp_lg_u64 s[30:31], 0
	v_lshl_add_u32 v0, v190, 12, v0
	v_and_b32_e32 v1, 1, v189
	s_cselect_b64 s[18:19], -1, 0
	s_lshl_b32 s0, s68, 2
	v_lshl_or_b32 v0, v1, 6, v0
	s_add_i32 s55, s0, 0
	v_mov_b32_e32 v158, 0
	v_lshl_add_u32 v160, v191, 1, v0
	s_add_i32 s56, 0, 0x10000
	s_add_i32 s57, 0, 0x14000
	s_add_i32 s58, 0, 0x18000
	s_add_i32 s59, 0, 0x1c000
	v_mbcnt_lo_u32_b32 v0, -1, 0
	s_mov_b32 s54, 0
	s_add_i32 s55, s55, 0x20000
	v_mov_b32_e32 v157, v158
	v_mov_b32_e32 v161, v158
	v_add_u32_e32 v176, s56, v192
	v_add_u32_e32 v177, s57, v192
	v_add_u32_e32 v178, 0, v193
	v_add_u32_e32 v179, s58, v192
	v_add_u32_e32 v180, s59, v192
	s_mov_b32 s20, 0x3e6d3388
	s_mov_b32 s22, 0x3f07dc22
	s_mov_b32 s34, 0xbf3a00e3
	s_mov_b32 s36, 0x3f35f0e3
	s_mov_b32 s38, 0xbe11a98e
	s_mov_b32 s40, 0x3e027906
	s_mov_b32 s42, 0xbf38aa3b
	v_mbcnt_hi_u32_b32 v181, -1, v0
	s_lshr_b32 s100, s88, 2
	s_cmp_lg_u32 s100, 1
	s_cbranch_scc1 .Lpro_lag1
	s_barrier
.Lpro_lag1:
	s_branch .LBB0_253

.LBB0_286:
	s_andn2_b64 vcc, exec, s[0:1]
	s_cbranch_vccnz .LBB0_366
	s_bfe_u32 s75, s49, 0x20003
	s_lshl_b32 s0, s64, 2
	s_or_b32 s73, s0, s75
	s_lshl_b32 s0, s73, 20
	s_add_u32 s34, s21, s0
	s_addc_u32 s35, s23, 0
	s_movk_i32 s0, 0x100
	v_cmp_gt_i32_e64 s[2:3], s0, v146
	v_mov_b32_e32 v151, 0
	s_add_u32 s0, s34, 0x80000
	v_mov_b32_e32 v149, v151
	v_mov_b32_e32 v153, v151
	s_addc_u32 s1, s35, 0
	v_lshl_add_u64 v[160:161], s[34:35], 0, v[148:149]
	v_lshl_add_u64 v[162:163], s[34:35], 0, v[152:153]
	v_lshl_add_u64 v[166:167], s[0:1], 0, v[148:149]
	v_lshl_add_u64 v[164:165], s[0:1], 0, v[152:153]
	s_cmp_eq_u32 s37, 1
	s_mov_b64 s[0:1], 0x80
	s_cselect_b64 s[40:41], -1, 0
	v_lshl_add_u64 v[158:159], v[160:161], 0, s[0:1]
	v_lshl_add_u64 v[156:157], v[162:163], 0, s[0:1]
	s_add_i32 s0, 0, 0x20000
	s_cmpk_lt_u32 s33, 0x100
	s_cselect_b64 s[38:39], -1, 0
	s_lshl_b32 s72, s43, 1
	v_lshl_add_u32 v0, s73, 8, v146
	s_waitcnt lgkmcnt(0)
	s_cmp_lg_u64 s[30:31], 0
	v_ashrrev_i32_e32 v1, 31, v0
	s_cselect_b64 s[36:37], -1, 0
	s_lshl_b32 s1, s68, 2
	v_lshlrev_b64 v[0:1], 8, v[0:1]
	s_add_i32 s74, s0, s1
	s_orn2_b32 s72, s72, 63
	v_lshl_add_u64 v[168:169], s[4:5], 0, v[0:1]
	v_mov_b32_e32 v155, v151
	s_cmp_gt_u32 s63, 63
	v_lshl_add_u32 v194, v146, 2, s0
	s_cbranch_scc1 .LBB0_323
	s_and_saveexec_b64 s[0:1], s[2:3]
	s_cbranch_execz .LBB0_290
	global_load_dwordx4 v[248:251], v[168:169], off offset:64
	global_load_dwordx4 v[244:247], v[168:169], off
	global_load_dwordx4 v[240:243], v[168:169], off offset:16
	global_load_dwordx4 v[236:239], v[168:169], off offset:80
	global_load_dwordx4 v[232:235], v[168:169], off offset:96
	global_load_dwordx4 v[228:231], v[168:169], off offset:32
	global_load_dwordx4 v[224:227], v[168:169], off offset:48
	global_load_dwordx4 v[220:223], v[168:169], off offset:112

.LBB0_292:
	s_mov_b64 s[4:5], 0x80
	v_lshl_add_u64 v[16:17], v[16:17], 0, s[4:5]
	s_add_i32 m0, s14, 0x18000
	global_load_lds_dwordx4 v[16:17], off
	v_lshl_add_u64 v[16:17], v[18:19], 0, s[4:5]
	s_add_i32 m0, s14, 0x1a000
	s_add_i32 s19, s14, 0x8000
	s_add_i32 s20, s14, 0xa000
	global_load_lds_dwordx4 v[16:17], off
	s_mov_b32 m0, s19
	s_add_u32 s6, s0, 0x80080
	global_load_lds_dwordx4 v[158:159], off
	s_mov_b32 m0, s20
	s_addc_u32 s7, s1, 0
	global_load_lds_dwordx4 v[156:157], off
	v_lshl_add_u64 v[16:17], s[6:7], 0, v[150:151]
	s_add_i32 m0, s14, 0x1c000
	s_nop 0
	global_load_lds_dwordx4 v[16:17], off
	v_lshl_add_u64 v[16:17], s[6:7], 0, v[154:155]
	s_add_i32 m0, s14, 0x1e000
	s_nop 0
	global_load_lds_dwordx4 v[16:17], off
	s_waitcnt vmcnt(6)
	s_barrier
	s_and_saveexec_b64 s[6:7], s[2:3]
	s_cbranch_execz .LBB0_294
	v_pk_add_f32 v[8:9], v[246:247], v[250:251]
	v_pk_add_f32 v[12:13], v[244:245], v[248:249]
	v_pk_add_f32 v[10:11], v[242:243], v[238:239]
	v_pk_add_f32 v[14:15], v[240:241], v[236:237]
	v_pk_add_f32 v[0:1], v[230:231], v[234:235]
	v_pk_add_f32 v[4:5], v[228:229], v[232:233]
	v_pk_add_f32 v[2:3], v[226:227], v[222:223]
	v_pk_add_f32 v[6:7], v[224:225], v[220:221]
	v_pk_add_f32 v[12:13], v[14:15], v[12:13]
	v_pk_add_f32 v[8:9], v[10:11], v[8:9]
	v_pk_add_f32 v[4:5], v[6:7], v[4:5]
	v_pk_add_f32 v[0:1], v[2:3], v[0:1]
	v_pk_add_f32 v[2:3], v[4:5], v[12:13]
	v_pk_add_f32 v[0:1], v[0:1], v[8:9]
	s_nop 0
	v_pk_mov_b32 v[4:5], v[2:3], v[0:1] op_sel:[1,0]
	v_mov_b32_e32 v3, v1
	v_pk_add_f32 v[0:1], v[4:5], v[2:3]
	s_nop 0
	v_add_f32_e32 v0, v0, v1
	v_mov_b32_e32 v1, 0x358637bd
	v_fmac_f32_e32 v1, 0x3a000000, v0
	v_rsq_f32_e32 v0, v1
	ds_write_b32 v194, v0
.LBB0_294:
	s_or_b64 exec, exec, s[6:7]
	v_lshlrev_b32_e32 v0, 15, v186
	s_lshl_b32 s6, s64, 22
	s_lshl_b32 s7, s75, 20
	v_and_b32_e32 v0, 0xffff0000, v0
	s_or_b32 s6, s6, s7
	v_lshl_add_u32 v0, v187, 12, v0
	v_and_b32_e32 v1, 1, v186
	s_add_u32 s6, s94, s6
	v_lshl_or_b32 v0, v1, 6, v0
	s_addc_u32 s7, s95, 0
	v_lshl_add_u32 v0, v188, 1, v0
	v_mov_b32_e32 v1, 0
	v_lshl_add_u64 v[2:3], s[6:7], 0, v[0:1]
	v_lshlrev_b32_e32 v0, 15, v189
	s_mov_b64 s[10:11], 0xf280080
	v_and_b32_e32 v0, 0xffff0000, v0
	s_add_u32 s8, s94, s8
	v_lshl_add_u64 v[40:41], v[2:3], 0, s[10:11]
	v_lshl_add_u32 v0, v190, 12, v0
	v_and_b32_e32 v2, 1, v189
	s_addc_u32 s9, s95, 0
	v_lshl_or_b32 v0, v2, 6, v0
	s_add_u32 s21, s8, 0x200100
	v_lshl_add_u32 v0, v191, 1, v0
	s_addc_u32 s22, s9, 0
	s_add_i32 s44, 0, 0x10000
	s_add_i32 s46, 0, 0x14000
	s_add_i32 s49, 0, 0x18000
	s_add_i32 s51, 0, 0x1c000
	v_lshl_add_u64 v[2:3], s[6:7], 0, v[0:1]
	v_add_u32_e32 v44, s44, v192
	v_add_u32_e32 v45, s46, v192
	s_add_i32 s44, s44, s66
	s_add_i32 s46, s46, s66
	v_add_u32_e32 v47, s49, v192
	v_add_u32_e32 v48, s51, v192
	s_add_i32 s49, s49, s66
	s_add_i32 s51, s51, s66
	v_lshl_add_u64 v[42:43], v[2:3], 0, s[10:11]
	s_mov_b32 s23, -2
	s_mov_b64 s[8:9], 0
	v_add_u32_e32 v46, 0, v193
	s_add_i32 s42, s14, 0xc000
	s_add_i32 s43, s14, 0xe000
	s_add_i32 s45, s44, 0x2000
	s_add_i32 s47, s46, 0x2000
	s_add_i32 s50, s49, 0x2000
	s_add_i32 s52, s51, 0x2000
	v_mov_b32_e32 v0, v1
	v_mov_b32_e32 v2, v1
	v_mov_b32_e32 v3, v1
	v_mov_b32_e32 v4, v1
	v_mov_b32_e32 v5, v1
	v_mov_b32_e32 v6, v1
	v_mov_b32_e32 v7, v1
	v_mov_b32_e32 v16, v1
	v_mov_b32_e32 v17, v1
	v_mov_b32_e32 v18, v1
	v_mov_b32_e32 v19, v1
	v_mov_b32_e32 v20, v1
	v_mov_b32_e32 v21, v1
	v_mov_b32_e32 v22, v1
	v_mov_b32_e32 v23, v1
	v_mov_b32_e32 v32, v1
	v_mov_b32_e32 v33, v1
	v_mov_b32_e32 v34, v1
	v_mov_b32_e32 v35, v1
	v_mov_b32_e32 v36, v1
	v_mov_b32_e32 v37, v1
	v_mov_b32_e32 v38, v1
	v_mov_b32_e32 v39, v1
	v_mov_b32_e32 v64, v1
	v_mov_b32_e32 v65, v1
	v_mov_b32_e32 v66, v1
	v_mov_b32_e32 v67, v1
	v_mov_b32_e32 v68, v1
	v_mov_b32_e32 v69, v1
	v_mov_b32_e32 v70, v1
	v_mov_b32_e32 v71, v1
	v_mov_b32_e32 v8, v1
	v_mov_b32_e32 v9, v1
	v_mov_b32_e32 v10, v1
	v_mov_b32_e32 v11, v1
	v_mov_b32_e32 v12, v1
	v_mov_b32_e32 v13, v1
	v_mov_b32_e32 v14, v1
	v_mov_b32_e32 v15, v1
	v_mov_b32_e32 v24, v1
	v_mov_b32_e32 v25, v1
	v_mov_b32_e32 v26, v1
	v_mov_b32_e32 v27, v1
	v_mov_b32_e32 v28, v1
	v_mov_b32_e32 v29, v1
	v_mov_b32_e32 v30, v1
	v_mov_b32_e32 v31, v1
	v_mov_b32_e32 v56, v1
	v_mov_b32_e32 v57, v1
	v_mov_b32_e32 v58, v1
	v_mov_b32_e32 v59, v1
	v_mov_b32_e32 v60, v1
	v_mov_b32_e32 v61, v1
	v_mov_b32_e32 v62, v1
	v_mov_b32_e32 v63, v1
	v_mov_b32_e32 v72, v1
	v_mov_b32_e32 v73, v1
	v_mov_b32_e32 v74, v1
	v_mov_b32_e32 v75, v1
	v_mov_b32_e32 v76, v1
	v_mov_b32_e32 v77, v1
	v_mov_b32_e32 v78, v1
	v_mov_b32_e32 v79, v1
	v_mov_b32_e32 v80, v1
	v_mov_b32_e32 v81, v1
	v_mov_b32_e32 v82, v1
	v_mov_b32_e32 v83, v1
	v_mov_b32_e32 v84, v1
	v_mov_b32_e32 v85, v1
	v_mov_b32_e32 v86, v1
	v_mov_b32_e32 v87, v1
	v_mov_b32_e32 v96, v1
	v_mov_b32_e32 v97, v1
	v_mov_b32_e32 v98, v1
	v_mov_b32_e32 v99, v1
	v_mov_b32_e32 v100, v1
	v_mov_b32_e32 v101, v1
	v_mov_b32_e32 v102, v1
	v_mov_b32_e32 v103, v1
	v_mov_b32_e32 v112, v1
	v_mov_b32_e32 v113, v1
	v_mov_b32_e32 v114, v1
	v_mov_b32_e32 v115, v1
	v_mov_b32_e32 v116, v1
	v_mov_b32_e32 v117, v1
	v_mov_b32_e32 v118, v1
	v_mov_b32_e32 v119, v1
	v_mov_b32_e32 v128, v1
	v_mov_b32_e32 v129, v1
	v_mov_b32_e32 v130, v1
	v_mov_b32_e32 v131, v1
	v_mov_b32_e32 v132, v1
	v_mov_b32_e32 v133, v1
	v_mov_b32_e32 v134, v1
	v_mov_b32_e32 v135, v1
	v_mov_b32_e32 v88, v1
	v_mov_b32_e32 v89, v1
	v_mov_b32_e32 v90, v1
	v_mov_b32_e32 v91, v1
	v_mov_b32_e32 v92, v1
	v_mov_b32_e32 v93, v1
	v_mov_b32_e32 v94, v1
	v_mov_b32_e32 v95, v1
	v_mov_b32_e32 v104, v1
	v_mov_b32_e32 v105, v1
	v_mov_b32_e32 v106, v1
	v_mov_b32_e32 v107, v1
	v_mov_b32_e32 v108, v1
	v_mov_b32_e32 v109, v1
	v_mov_b32_e32 v110, v1
	v_mov_b32_e32 v111, v1
	v_mov_b32_e32 v120, v1
	v_mov_b32_e32 v121, v1
	v_mov_b32_e32 v122, v1
	v_mov_b32_e32 v123, v1
	v_mov_b32_e32 v124, v1
	v_mov_b32_e32 v125, v1
	v_mov_b32_e32 v126, v1
	v_mov_b32_e32 v127, v1
	v_mov_b32_e32 v136, v1
	v_mov_b32_e32 v137, v1
	v_mov_b32_e32 v138, v1
	v_mov_b32_e32 v139, v1
	v_mov_b32_e32 v140, v1
	v_mov_b32_e32 v141, v1
	v_mov_b32_e32 v142, v1
	v_mov_b32_e32 v143, v1
	s_lshr_b32 s100, s88, 2
	s_cmp_lg_u32 s100, 1
	s_cbranch_scc1 .Lpro_lag2
	s_barrier
.Lpro_lag2:
.LBB0_295:
	ds_read_b128 v[50:53], v44
	ds_read_b128 v[170:173], v44 offset:1024
	ds_read_b128 v[174:177], v44 offset:2048
	ds_read_b128 v[178:181], v44 offset:3072
	ds_read_b128 v[196:199], v45
	ds_read_b128 v[200:203], v45 offset:1024
	ds_read_b128 v[204:207], v45 offset:2048
	ds_read_b128 v[208:211], v45 offset:3072
	s_add_u32 s10, s6, s8
	s_addc_u32 s11, s7, s9
	s_add_u32 s10, s10, 0xf200100
	s_addc_u32 s11, s11, 0
	s_add_u32 s53, s21, s8
	s_addc_u32 s54, s22, s9
	s_cmpk_eq_i32 s8, 0xf00
	s_cselect_b32 s13, s35, s11
	s_cselect_b32 s12, s34, s10
	s_cselect_b32 s11, s1, s54
	s_cselect_b32 s10, s0, s53
	s_mov_b32 m0, s42
	v_lshl_add_u64 v[54:55], v[40:41], 0, s[8:9]
	ds_read_b128 v[212:215], v46
	ds_read_b128 v[216:219], v46 offset:1024
	ds_read_b128 v[220:223], v46 offset:2048
	ds_read_b128 v[224:227], v46 offset:3072
	ds_read_b128 v[228:231], v46 offset:4096
	ds_read_b128 v[232:235], v46 offset:5120
	ds_read_b128 v[236:239], v46 offset:6144
	ds_read_b128 v[240:243], v46 offset:7168
	global_load_lds_dwordx4 v[54:55], off
	v_lshl_add_u64 v[54:55], v[42:43], 0, s[8:9]
	s_mov_b32 m0, s43
	s_nop 0
	global_load_lds_dwordx4 v[54:55], off
	s_waitcnt vmcnt(8)
	s_waitcnt lgkmcnt(0)
	s_barrier
	s_setprio 1
	s_waitcnt lgkmcnt(0)
	v_mfma_f32_16x16x32_bf16 v[140:143], v[50:53], v[212:215], v[140:143]
	v_mfma_f32_16x16x32_bf16 v[136:139], v[174:177], v[212:215], v[136:139]
	v_mfma_f32_16x16x32_bf16 v[124:127], v[50:53], v[220:223], v[124:127]
	v_mfma_f32_16x16x32_bf16 v[120:123], v[174:177], v[220:223], v[120:123]
	v_mfma_f32_16x16x32_bf16 v[108:111], v[50:53], v[228:231], v[108:111]
	v_mfma_f32_16x16x32_bf16 v[104:107], v[174:177], v[228:231], v[104:107]
	v_mfma_f32_16x16x32_bf16 v[92:95], v[50:53], v[236:239], v[92:95]
	v_mfma_f32_16x16x32_bf16 v[88:91], v[174:177], v[236:239], v[88:91]
	v_mfma_f32_16x16x32_bf16 v[140:143], v[170:173], v[216:219], v[140:143]
	v_mfma_f32_16x16x32_bf16 v[136:139], v[178:181], v[216:219], v[136:139]
	v_mfma_f32_16x16x32_bf16 v[124:127], v[170:173], v[224:227], v[124:127]
	v_mfma_f32_16x16x32_bf16 v[120:123], v[178:181], v[224:227], v[120:123]
	v_mfma_f32_16x16x32_bf16 v[108:111], v[170:173], v[232:235], v[108:111]
	v_mfma_f32_16x16x32_bf16 v[104:107], v[178:181], v[232:235], v[104:107]
	v_mfma_f32_16x16x32_bf16 v[92:95], v[170:173], v[240:243], v[92:95]
	v_mfma_f32_16x16x32_bf16 v[88:91], v[178:181], v[240:243], v[88:91]
	s_setprio 0
	s_setprio 1
	v_mfma_f32_16x16x32_bf16 v[132:135], v[196:199], v[212:215], v[132:135]
	v_mfma_f32_16x16x32_bf16 v[128:131], v[204:207], v[212:215], v[128:131]
	v_mfma_f32_16x16x32_bf16 v[116:119], v[196:199], v[220:223], v[116:119]
	v_mfma_f32_16x16x32_bf16 v[112:115], v[204:207], v[220:223], v[112:115]
	v_mfma_f32_16x16x32_bf16 v[100:103], v[196:199], v[228:231], v[100:103]
	v_mfma_f32_16x16x32_bf16 v[96:99], v[204:207], v[228:231], v[96:99]
	v_mfma_f32_16x16x32_bf16 v[84:87], v[196:199], v[236:239], v[84:87]
	v_mfma_f32_16x16x32_bf16 v[80:83], v[204:207], v[236:239], v[80:83]
	v_mfma_f32_16x16x32_bf16 v[132:135], v[200:203], v[216:219], v[132:135]
	v_mfma_f32_16x16x32_bf16 v[128:131], v[208:211], v[216:219], v[128:131]
	v_mfma_f32_16x16x32_bf16 v[116:119], v[200:203], v[224:227], v[116:119]
	v_mfma_f32_16x16x32_bf16 v[112:115], v[208:211], v[224:227], v[112:115]
	v_mfma_f32_16x16x32_bf16 v[100:103], v[200:203], v[232:235], v[100:103]
	v_mfma_f32_16x16x32_bf16 v[96:99], v[208:211], v[232:235], v[96:99]
	v_mfma_f32_16x16x32_bf16 v[84:87], v[200:203], v[240:243], v[84:87]
	v_mfma_f32_16x16x32_bf16 v[80:83], v[208:211], v[240:243], v[80:83]
	s_setprio 0
	s_barrier
	s_mov_b32 m0, s44
	v_lshl_add_u64 v[182:183], s[10:11], 0, v[150:151]
	s_add_u32 s54, s10, 0x80000
	ds_read_b128 v[212:215], v46 offset:16384
	ds_read_b128 v[216:219], v46 offset:17408
	ds_read_b128 v[220:223], v46 offset:18432
	ds_read_b128 v[224:227], v46 offset:19456
	ds_read_b128 v[228:231], v46 offset:20480
	ds_read_b128 v[232:235], v46 offset:21504
	ds_read_b128 v[236:239], v46 offset:22528
	ds_read_b128 v[240:243], v46 offset:23552
	global_load_lds_dwordx4 v[182:183], off
	v_lshl_add_u64 v[244:245], s[10:11], 0, v[154:155]
	s_mov_b32 m0, s45
	s_addc_u32 s55, s11, 0
	global_load_lds_dwordx4 v[244:245], off
	v_lshl_add_u64 v[54:55], s[54:55], 0, v[150:151]
	s_mov_b32 m0, s46
	v_lshl_add_u64 v[246:247], s[12:13], 0, v[148:149]
	global_load_lds_dwordx4 v[54:55], off
	v_lshl_add_u64 v[54:55], s[54:55], 0, v[154:155]
	s_mov_b32 m0, s47
	v_lshl_add_u64 v[248:249], s[12:13], 0, v[152:153]
	global_load_lds_dwordx4 v[54:55], off
	s_mov_b32 m0, s14
	s_nop 0
	global_load_lds_dwordx4 v[246:247], off
	s_mov_b32 m0, s16
	s_nop 0
	global_load_lds_dwordx4 v[248:249], off
	s_waitcnt vmcnt(8)
	s_waitcnt lgkmcnt(0)
	s_barrier
	s_setprio 1
	s_waitcnt lgkmcnt(0)
	v_mfma_f32_16x16x32_bf16 v[76:79], v[50:53], v[212:215], v[76:79]
	v_mfma_f32_16x16x32_bf16 v[72:75], v[174:177], v[212:215], v[72:75]
	v_mfma_f32_16x16x32_bf16 v[60:63], v[50:53], v[220:223], v[60:63]
	v_mfma_f32_16x16x32_bf16 v[54:57], v[174:177], v[220:223], v[56:59]
	v_mfma_f32_16x16x32_bf16 v[28:31], v[50:53], v[228:231], v[28:31]
	v_mfma_f32_16x16x32_bf16 v[24:27], v[174:177], v[228:231], v[24:27]
	v_mfma_f32_16x16x32_bf16 v[12:15], v[50:53], v[236:239], v[12:15]
	v_mfma_f32_16x16x32_bf16 v[8:11], v[174:177], v[236:239], v[8:11]
	v_mfma_f32_16x16x32_bf16 v[76:79], v[170:173], v[216:219], v[76:79]
	v_mfma_f32_16x16x32_bf16 v[72:75], v[178:181], v[216:219], v[72:75]
	v_mfma_f32_16x16x32_bf16 v[60:63], v[170:173], v[224:227], v[60:63]
	v_mfma_f32_16x16x32_bf16 v[54:57], v[178:181], v[224:227], v[54:57]
	v_mfma_f32_16x16x32_bf16 v[28:31], v[170:173], v[232:235], v[28:31]
	v_mfma_f32_16x16x32_bf16 v[24:27], v[178:181], v[232:235], v[24:27]
	v_mfma_f32_16x16x32_bf16 v[12:15], v[170:173], v[240:243], v[12:15]
	v_mfma_f32_16x16x32_bf16 v[8:11], v[178:181], v[240:243], v[8:11]
	s_setprio 0
	s_setprio 1
	v_mfma_f32_16x16x32_bf16 v[64:67], v[204:207], v[212:215], v[64:67]
	v_mfma_f32_16x16x32_bf16 v[36:39], v[196:199], v[220:223], v[36:39]
	v_mfma_f32_16x16x32_bf16 v[32:35], v[204:207], v[220:223], v[32:35]
	v_mfma_f32_16x16x32_bf16 v[20:23], v[196:199], v[228:231], v[20:23]
	v_mfma_f32_16x16x32_bf16 v[16:19], v[204:207], v[228:231], v[16:19]
	v_mfma_f32_16x16x32_bf16 v[4:7], v[196:199], v[236:239], v[4:7]
	v_mfma_f32_16x16x32_bf16 v[0:3], v[204:207], v[236:239], v[0:3]
	v_mfma_f32_16x16x32_bf16 v[50:53], v[196:199], v[212:215], v[68:71]
	v_mfma_f32_16x16x32_bf16 v[64:67], v[208:211], v[216:219], v[64:67]
	v_mfma_f32_16x16x32_bf16 v[36:39], v[200:203], v[224:227], v[36:39]
	v_mfma_f32_16x16x32_bf16 v[32:35], v[208:211], v[224:227], v[32:35]
	v_mfma_f32_16x16x32_bf16 v[20:23], v[200:203], v[232:235], v[20:23]
	v_mfma_f32_16x16x32_bf16 v[16:19], v[208:211], v[232:235], v[16:19]
	v_mfma_f32_16x16x32_bf16 v[4:7], v[200:203], v[240:243], v[4:7]
	v_mfma_f32_16x16x32_bf16 v[0:3], v[208:211], v[240:243], v[0:3]
	v_mfma_f32_16x16x32_bf16 v[50:53], v[200:203], v[216:219], v[50:53]
	s_setprio 0
	s_barrier
	ds_read_b128 v[68:71], v47
	ds_read_b128 v[170:173], v47 offset:1024
	ds_read_b128 v[174:177], v47 offset:2048
	ds_read_b128 v[178:181], v47 offset:3072
	ds_read_b128 v[196:199], v48
	ds_read_b128 v[200:203], v48 offset:1024
	ds_read_b128 v[204:207], v48 offset:2048
	ds_read_b128 v[208:211], v48 offset:3072
	s_add_u32 s12, s12, 0x80000
	s_addc_u32 s13, s13, 0
	s_mov_b32 m0, s17
	v_lshl_add_u64 v[58:59], s[12:13], 0, v[148:149]
	ds_read_b128 v[212:215], v46 offset:32768
	ds_read_b128 v[216:219], v46 offset:33792
	ds_read_b128 v[220:223], v46 offset:34816
	ds_read_b128 v[224:227], v46 offset:35840
	ds_read_b128 v[228:231], v46 offset:36864
	ds_read_b128 v[232:235], v46 offset:37888
	ds_read_b128 v[236:239], v46 offset:38912
	ds_read_b128 v[240:243], v46 offset:39936
	global_load_lds_dwordx4 v[58:59], off
	v_lshl_add_u64 v[58:59], s[12:13], 0, v[152:153]
	s_mov_b32 m0, s18
	s_nop 0
	global_load_lds_dwordx4 v[58:59], off
	s_waitcnt vmcnt(8)
	s_waitcnt lgkmcnt(0)
	s_barrier
	s_setprio 1
	s_waitcnt lgkmcnt(0)
	v_mfma_f32_16x16x32_bf16 v[140:143], v[68:71], v[212:215], v[140:143]
	v_mfma_f32_16x16x32_bf16 v[136:139], v[174:177], v[212:215], v[136:139]
	v_mfma_f32_16x16x32_bf16 v[124:127], v[68:71], v[220:223], v[124:127]
	v_mfma_f32_16x16x32_bf16 v[120:123], v[174:177], v[220:223], v[120:123]
	v_mfma_f32_16x16x32_bf16 v[108:111], v[68:71], v[228:231], v[108:111]
	v_mfma_f32_16x16x32_bf16 v[104:107], v[174:177], v[228:231], v[104:107]
	v_mfma_f32_16x16x32_bf16 v[92:95], v[68:71], v[236:239], v[92:95]
	v_mfma_f32_16x16x32_bf16 v[88:91], v[174:177], v[236:239], v[88:91]
	v_mfma_f32_16x16x32_bf16 v[140:143], v[170:173], v[216:219], v[140:143]
	v_mfma_f32_16x16x32_bf16 v[136:139], v[178:181], v[216:219], v[136:139]
	v_mfma_f32_16x16x32_bf16 v[124:127], v[170:173], v[224:227], v[124:127]
	v_mfma_f32_16x16x32_bf16 v[120:123], v[178:181], v[224:227], v[120:123]
	v_mfma_f32_16x16x32_bf16 v[108:111], v[170:173], v[232:235], v[108:111]
	v_mfma_f32_16x16x32_bf16 v[104:107], v[178:181], v[232:235], v[104:107]
	v_mfma_f32_16x16x32_bf16 v[92:95], v[170:173], v[240:243], v[92:95]
	v_mfma_f32_16x16x32_bf16 v[88:91], v[178:181], v[240:243], v[88:91]
	s_setprio 0
	s_setprio 1
	v_mfma_f32_16x16x32_bf16 v[132:135], v[196:199], v[212:215], v[132:135]
	v_mfma_f32_16x16x32_bf16 v[128:131], v[204:207], v[212:215], v[128:131]
	v_mfma_f32_16x16x32_bf16 v[116:119], v[196:199], v[220:223], v[116:119]
	v_mfma_f32_16x16x32_bf16 v[112:115], v[204:207], v[220:223], v[112:115]
	v_mfma_f32_16x16x32_bf16 v[100:103], v[196:199], v[228:231], v[100:103]
	v_mfma_f32_16x16x32_bf16 v[96:99], v[204:207], v[228:231], v[96:99]
	v_mfma_f32_16x16x32_bf16 v[84:87], v[196:199], v[236:239], v[84:87]
	v_mfma_f32_16x16x32_bf16 v[80:83], v[204:207], v[236:239], v[80:83]
	v_mfma_f32_16x16x32_bf16 v[132:135], v[200:203], v[216:219], v[132:135]
	v_mfma_f32_16x16x32_bf16 v[128:131], v[208:211], v[216:219], v[128:131]
	v_mfma_f32_16x16x32_bf16 v[116:119], v[200:203], v[224:227], v[116:119]
	v_mfma_f32_16x16x32_bf16 v[112:115], v[208:211], v[224:227], v[112:115]
	v_mfma_f32_16x16x32_bf16 v[100:103], v[200:203], v[232:235], v[100:103]
	v_mfma_f32_16x16x32_bf16 v[96:99], v[208:211], v[232:235], v[96:99]
	v_mfma_f32_16x16x32_bf16 v[84:87], v[200:203], v[240:243], v[84:87]
	v_mfma_f32_16x16x32_bf16 v[80:83], v[208:211], v[240:243], v[80:83]
	s_setprio 0
	s_barrier
	s_mov_b32 m0, s49
	v_lshl_add_u64 v[58:59], v[182:183], 0, s[4:5]
	s_add_u32 s10, s10, 0x80080
	ds_read_b128 v[212:215], v46 offset:49152
	ds_read_b128 v[216:219], v46 offset:50176
	ds_read_b128 v[220:223], v46 offset:51200
	ds_read_b128 v[224:227], v46 offset:52224
	ds_read_b128 v[228:231], v46 offset:53248
	ds_read_b128 v[232:235], v46 offset:54272
	ds_read_b128 v[236:239], v46 offset:55296
	ds_read_b128 v[240:243], v46 offset:56320
	global_load_lds_dwordx4 v[58:59], off
	v_lshl_add_u64 v[58:59], v[244:245], 0, s[4:5]
	s_mov_b32 m0, s50
	s_addc_u32 s11, s11, 0
	global_load_lds_dwordx4 v[58:59], off
	v_lshl_add_u64 v[58:59], s[10:11], 0, v[150:151]
	s_mov_b32 m0, s51
	s_nop 0
	global_load_lds_dwordx4 v[58:59], off
	v_lshl_add_u64 v[58:59], s[10:11], 0, v[154:155]
	s_mov_b32 m0, s52
	s_nop 0
	global_load_lds_dwordx4 v[58:59], off
	v_lshl_add_u64 v[58:59], v[246:247], 0, s[4:5]
	s_mov_b32 m0, s19
	s_nop 0
	global_load_lds_dwordx4 v[58:59], off
	v_lshl_add_u64 v[58:59], v[248:249], 0, s[4:5]
	s_mov_b32 m0, s20
	s_nop 0
	global_load_lds_dwordx4 v[58:59], off
	s_waitcnt vmcnt(8)
	s_waitcnt lgkmcnt(0)
	s_barrier
	s_setprio 1
	s_waitcnt lgkmcnt(0)
	v_mfma_f32_16x16x32_bf16 v[76:79], v[68:71], v[212:215], v[76:79]
	v_mfma_f32_16x16x32_bf16 v[72:75], v[174:177], v[212:215], v[72:75]
	v_mfma_f32_16x16x32_bf16 v[58:61], v[68:71], v[220:223], v[60:63]
	v_mfma_f32_16x16x32_bf16 v[54:57], v[174:177], v[220:223], v[54:57]
	v_mfma_f32_16x16x32_bf16 v[28:31], v[68:71], v[228:231], v[28:31]
	v_mfma_f32_16x16x32_bf16 v[24:27], v[174:177], v[228:231], v[24:27]
	v_mfma_f32_16x16x32_bf16 v[12:15], v[68:71], v[236:239], v[12:15]
	v_mfma_f32_16x16x32_bf16 v[8:11], v[174:177], v[236:239], v[8:11]
	v_mfma_f32_16x16x32_bf16 v[76:79], v[170:173], v[216:219], v[76:79]
	v_mfma_f32_16x16x32_bf16 v[72:75], v[178:181], v[216:219], v[72:75]
	v_mfma_f32_16x16x32_bf16 v[60:63], v[170:173], v[224:227], v[58:61]
	v_mfma_f32_16x16x32_bf16 v[56:59], v[178:181], v[224:227], v[54:57]
	v_mfma_f32_16x16x32_bf16 v[28:31], v[170:173], v[232:235], v[28:31]
	v_mfma_f32_16x16x32_bf16 v[24:27], v[178:181], v[232:235], v[24:27]
	v_mfma_f32_16x16x32_bf16 v[12:15], v[170:173], v[240:243], v[12:15]
	v_mfma_f32_16x16x32_bf16 v[8:11], v[178:181], v[240:243], v[8:11]
	s_setprio 0
	s_setprio 1
	v_mfma_f32_16x16x32_bf16 v[50:53], v[196:199], v[212:215], v[50:53]
	v_mfma_f32_16x16x32_bf16 v[68:71], v[200:203], v[216:219], v[50:53]
	v_mfma_f32_16x16x32_bf16 v[50:53], v[204:207], v[212:215], v[64:67]
	v_mfma_f32_16x16x32_bf16 v[36:39], v[196:199], v[220:223], v[36:39]
	v_mfma_f32_16x16x32_bf16 v[32:35], v[204:207], v[220:223], v[32:35]
	v_mfma_f32_16x16x32_bf16 v[20:23], v[196:199], v[228:231], v[20:23]
	v_mfma_f32_16x16x32_bf16 v[16:19], v[204:207], v[228:231], v[16:19]
	v_mfma_f32_16x16x32_bf16 v[4:7], v[196:199], v[236:239], v[4:7]
	v_mfma_f32_16x16x32_bf16 v[0:3], v[204:207], v[236:239], v[0:3]
	v_mfma_f32_16x16x32_bf16 v[64:67], v[208:211], v[216:219], v[50:53]
	v_mfma_f32_16x16x32_bf16 v[36:39], v[200:203], v[224:227], v[36:39]
	v_mfma_f32_16x16x32_bf16 v[32:35], v[208:211], v[224:227], v[32:35]
	v_mfma_f32_16x16x32_bf16 v[20:23], v[200:203], v[232:235], v[20:23]
	v_mfma_f32_16x16x32_bf16 v[16:19], v[208:211], v[232:235], v[16:19]
	v_mfma_f32_16x16x32_bf16 v[4:7], v[200:203], v[240:243], v[4:7]
	v_mfma_f32_16x16x32_bf16 v[0:3], v[208:211], v[240:243], v[0:3]
	s_setprio 0
	s_barrier
	s_add_i32 s23, s23, 2
	s_add_u32 s8, s8, 0x100
	s_addc_u32 s9, s9, 0
	s_cmp_gt_u32 s23, 29
	s_cbranch_scc0 .LBB0_295
	s_and_b64 vcc, exec, s[38:39]
	s_cbranch_vccz .LBB0_298
	s_barrier

.LBB0_330:
	s_waitcnt vmcnt(0)
	s_cmp_gt_u32 s63, 31
	s_waitcnt lgkmcnt(0)
	s_barrier
	s_cbranch_scc1 .LBB0_366
	s_and_saveexec_b64 s[0:1], s[2:3]
	s_cbranch_execz .LBB0_333
	global_load_dwordx4 v[248:251], v[168:169], off offset:64
	global_load_dwordx4 v[244:247], v[168:169], off
	global_load_dwordx4 v[240:243], v[168:169], off offset:16
	global_load_dwordx4 v[236:239], v[168:169], off offset:80
	global_load_dwordx4 v[232:235], v[168:169], off offset:96
	global_load_dwordx4 v[228:231], v[168:169], off offset:32
	global_load_dwordx4 v[224:227], v[168:169], off offset:48
	global_load_dwordx4 v[220:223], v[168:169], off offset:112

.LBB0_335:
	s_mov_b64 s[4:5], 0x80
	v_lshl_add_u64 v[16:17], v[16:17], 0, s[4:5]
	s_add_i32 m0, s12, 0x18000
	global_load_lds_dwordx4 v[16:17], off
	v_lshl_add_u64 v[16:17], v[18:19], 0, s[4:5]
	s_add_i32 m0, s12, 0x1a000
	s_add_i32 s17, s12, 0x8000
	s_add_i32 s18, s12, 0xa000
	global_load_lds_dwordx4 v[16:17], off
	s_mov_b32 m0, s17
	s_add_u32 s6, s0, 0x80080
	global_load_lds_dwordx4 v[158:159], off
	s_mov_b32 m0, s18
	s_addc_u32 s7, s1, 0
	global_load_lds_dwordx4 v[156:157], off
	v_lshl_add_u64 v[16:17], s[6:7], 0, v[150:151]
	s_add_i32 m0, s12, 0x1c000
	s_nop 0
	global_load_lds_dwordx4 v[16:17], off
	v_lshl_add_u64 v[16:17], s[6:7], 0, v[154:155]
	s_add_i32 m0, s12, 0x1e000
	s_nop 0
	global_load_lds_dwordx4 v[16:17], off
	s_waitcnt vmcnt(6)
	s_barrier
	s_and_saveexec_b64 s[6:7], s[2:3]
	s_cbranch_execz .LBB0_337
	v_pk_add_f32 v[8:9], v[246:247], v[250:251]
	v_pk_add_f32 v[12:13], v[244:245], v[248:249]
	v_pk_add_f32 v[10:11], v[242:243], v[238:239]
	v_pk_add_f32 v[14:15], v[240:241], v[236:237]
	v_pk_add_f32 v[0:1], v[230:231], v[234:235]
	v_pk_add_f32 v[4:5], v[228:229], v[232:233]
	v_pk_add_f32 v[2:3], v[226:227], v[222:223]
	v_pk_add_f32 v[6:7], v[224:225], v[220:221]
	v_pk_add_f32 v[12:13], v[14:15], v[12:13]
	v_pk_add_f32 v[8:9], v[10:11], v[8:9]
	v_pk_add_f32 v[4:5], v[6:7], v[4:5]
	v_pk_add_f32 v[0:1], v[2:3], v[0:1]
	v_pk_add_f32 v[2:3], v[4:5], v[12:13]
	v_pk_add_f32 v[0:1], v[0:1], v[8:9]
	s_nop 0
	v_pk_mov_b32 v[4:5], v[2:3], v[0:1] op_sel:[1,0]
	v_mov_b32_e32 v3, v1
	v_pk_add_f32 v[0:1], v[4:5], v[2:3]
	s_nop 0
	v_add_f32_e32 v0, v0, v1
	v_mov_b32_e32 v1, 0x358637bd
	v_fmac_f32_e32 v1, 0x3a000000, v0
	v_rsq_f32_e32 v0, v1
	ds_write_b32 v194, v0
.LBB0_337:
	s_or_b64 exec, exec, s[6:7]
	v_lshlrev_b32_e32 v0, 15, v186
	s_lshl_b32 s2, s64, 22
	s_lshl_b32 s3, s75, 20
	v_and_b32_e32 v0, 0xffff0000, v0
	s_or_b32 s2, s2, s3
	v_lshl_add_u32 v0, v187, 12, v0
	v_and_b32_e32 v1, 1, v186
	s_add_u32 s2, s94, s2
	v_lshl_or_b32 v0, v1, 6, v0
	s_addc_u32 s3, s95, 0
	v_lshl_add_u32 v0, v188, 1, v0
	v_mov_b32_e32 v1, 0
	v_lshl_add_u64 v[2:3], s[2:3], 0, v[0:1]
	v_lshlrev_b32_e32 v0, 15, v189
	s_mov_b64 s[6:7], 0xf280080
	v_and_b32_e32 v0, 0xffff0000, v0
	v_lshl_add_u64 v[40:41], v[2:3], 0, s[6:7]
	v_lshl_add_u32 v0, v190, 12, v0
	v_and_b32_e32 v2, 1, v189
	v_lshl_or_b32 v0, v2, 6, v0
	v_lshl_add_u32 v0, v191, 1, v0
	v_lshl_add_u64 v[2:3], s[2:3], 0, v[0:1]
	v_lshl_add_u64 v[42:43], v[2:3], 0, s[6:7]
	s_add_u32 s6, s94, s8
	s_addc_u32 s7, s95, 0
	s_add_u32 s19, s6, 0x200100
	s_addc_u32 s20, s7, 0
	s_add_i32 s40, 0, 0x10000
	s_add_i32 s42, 0, 0x14000
	s_add_i32 s44, 0, 0x18000
	s_add_i32 s46, 0, 0x1c000
	v_add_u32_e32 v44, s40, v192
	v_add_u32_e32 v45, s42, v192
	s_add_i32 s40, s40, s66
	s_add_i32 s42, s42, s66
	v_add_u32_e32 v47, s44, v192
	v_add_u32_e32 v48, s46, v192
	s_add_i32 s44, s44, s66
	s_add_i32 s46, s46, s66
	s_mov_b32 s21, -2
	s_mov_b64 s[6:7], 0
	v_add_u32_e32 v46, 0, v193
	s_add_i32 s22, s12, 0xc000
	s_add_i32 s23, s12, 0xe000
	s_add_i32 s41, s40, 0x2000
	s_add_i32 s43, s42, 0x2000
	s_add_i32 s45, s44, 0x2000
	s_add_i32 s47, s46, 0x2000
	v_mov_b32_e32 v0, v1
	v_mov_b32_e32 v2, v1
	v_mov_b32_e32 v3, v1
	v_mov_b32_e32 v4, v1
	v_mov_b32_e32 v5, v1
	v_mov_b32_e32 v6, v1
	v_mov_b32_e32 v7, v1
	v_mov_b32_e32 v16, v1
	v_mov_b32_e32 v17, v1
	v_mov_b32_e32 v18, v1
	v_mov_b32_e32 v19, v1
	v_mov_b32_e32 v20, v1
	v_mov_b32_e32 v21, v1
	v_mov_b32_e32 v22, v1
	v_mov_b32_e32 v23, v1
	v_mov_b32_e32 v32, v1
	v_mov_b32_e32 v33, v1
	v_mov_b32_e32 v34, v1
	v_mov_b32_e32 v35, v1
	v_mov_b32_e32 v36, v1
	v_mov_b32_e32 v37, v1
	v_mov_b32_e32 v38, v1
	v_mov_b32_e32 v39, v1
	v_mov_b32_e32 v64, v1
	v_mov_b32_e32 v65, v1
	v_mov_b32_e32 v66, v1
	v_mov_b32_e32 v67, v1
	v_mov_b32_e32 v68, v1
	v_mov_b32_e32 v69, v1
	v_mov_b32_e32 v70, v1
	v_mov_b32_e32 v71, v1
	v_mov_b32_e32 v8, v1
	v_mov_b32_e32 v9, v1
	v_mov_b32_e32 v10, v1
	v_mov_b32_e32 v11, v1
	v_mov_b32_e32 v12, v1
	v_mov_b32_e32 v13, v1
	v_mov_b32_e32 v14, v1
	v_mov_b32_e32 v15, v1
	v_mov_b32_e32 v24, v1
	v_mov_b32_e32 v25, v1
	v_mov_b32_e32 v26, v1
	v_mov_b32_e32 v27, v1
	v_mov_b32_e32 v28, v1
	v_mov_b32_e32 v29, v1
	v_mov_b32_e32 v30, v1
	v_mov_b32_e32 v31, v1
	v_mov_b32_e32 v56, v1
	v_mov_b32_e32 v57, v1
	v_mov_b32_e32 v58, v1
	v_mov_b32_e32 v59, v1
	v_mov_b32_e32 v60, v1
	v_mov_b32_e32 v61, v1
	v_mov_b32_e32 v62, v1
	v_mov_b32_e32 v63, v1
	v_mov_b32_e32 v72, v1
	v_mov_b32_e32 v73, v1
	v_mov_b32_e32 v74, v1
	v_mov_b32_e32 v75, v1
	v_mov_b32_e32 v76, v1
	v_mov_b32_e32 v77, v1
	v_mov_b32_e32 v78, v1
	v_mov_b32_e32 v79, v1
	v_mov_b32_e32 v80, v1
	v_mov_b32_e32 v81, v1
	v_mov_b32_e32 v82, v1
	v_mov_b32_e32 v83, v1
	v_mov_b32_e32 v84, v1
	v_mov_b32_e32 v85, v1
	v_mov_b32_e32 v86, v1
	v_mov_b32_e32 v87, v1
	v_mov_b32_e32 v96, v1
	v_mov_b32_e32 v97, v1
	v_mov_b32_e32 v98, v1
	v_mov_b32_e32 v99, v1
	v_mov_b32_e32 v100, v1
	v_mov_b32_e32 v101, v1
	v_mov_b32_e32 v102, v1
	v_mov_b32_e32 v103, v1
	v_mov_b32_e32 v112, v1
	v_mov_b32_e32 v113, v1
	v_mov_b32_e32 v114, v1
	v_mov_b32_e32 v115, v1
	v_mov_b32_e32 v116, v1
	v_mov_b32_e32 v117, v1
	v_mov_b32_e32 v118, v1
	v_mov_b32_e32 v119, v1
	v_mov_b32_e32 v128, v1
	v_mov_b32_e32 v129, v1
	v_mov_b32_e32 v130, v1
	v_mov_b32_e32 v131, v1
	v_mov_b32_e32 v132, v1
	v_mov_b32_e32 v133, v1
	v_mov_b32_e32 v134, v1
	v_mov_b32_e32 v135, v1
	v_mov_b32_e32 v88, v1
	v_mov_b32_e32 v89, v1
	v_mov_b32_e32 v90, v1
	v_mov_b32_e32 v91, v1
	v_mov_b32_e32 v92, v1
	v_mov_b32_e32 v93, v1
	v_mov_b32_e32 v94, v1
	v_mov_b32_e32 v95, v1
	v_mov_b32_e32 v104, v1
	v_mov_b32_e32 v105, v1
	v_mov_b32_e32 v106, v1
	v_mov_b32_e32 v107, v1
	v_mov_b32_e32 v108, v1
	v_mov_b32_e32 v109, v1
	v_mov_b32_e32 v110, v1
	v_mov_b32_e32 v111, v1
	v_mov_b32_e32 v120, v1
	v_mov_b32_e32 v121, v1
	v_mov_b32_e32 v122, v1
	v_mov_b32_e32 v123, v1
	v_mov_b32_e32 v124, v1
	v_mov_b32_e32 v125, v1
	v_mov_b32_e32 v126, v1
	v_mov_b32_e32 v127, v1
	v_mov_b32_e32 v136, v1
	v_mov_b32_e32 v137, v1
	v_mov_b32_e32 v138, v1
	v_mov_b32_e32 v139, v1
	v_mov_b32_e32 v140, v1
	v_mov_b32_e32 v141, v1
	v_mov_b32_e32 v142, v1
	v_mov_b32_e32 v143, v1
	s_lshr_b32 s100, s88, 2
	s_cmp_lg_u32 s100, 1
	s_cbranch_scc1 .Lpro_lag3
	s_barrier
.Lpro_lag3:
.LBB0_338:
	ds_read_b128 v[50:53], v44
	ds_read_b128 v[156:159], v44 offset:1024
	ds_read_b128 v[160:163], v44 offset:2048
	ds_read_b128 v[164:167], v44 offset:3072
	ds_read_b128 v[168:171], v45
	ds_read_b128 v[172:175], v45 offset:1024
	ds_read_b128 v[176:179], v45 offset:2048
	ds_read_b128 v[180:183], v45 offset:3072
	s_add_u32 s8, s2, s6
	s_addc_u32 s9, s3, s7
	s_add_u32 s8, s8, 0xf200100
	s_addc_u32 s9, s9, 0
	s_add_u32 s48, s19, s6
	s_addc_u32 s49, s20, s7
	s_cmpk_eq_i32 s6, 0xf00
	s_cselect_b32 s11, s35, s9
	s_cselect_b32 s10, s34, s8
	s_cselect_b32 s9, s1, s49
	s_cselect_b32 s8, s0, s48
	s_mov_b32 m0, s22
	v_lshl_add_u64 v[54:55], v[40:41], 0, s[6:7]
	ds_read_b128 v[186:189], v46
	ds_read_b128 v[190:193], v46 offset:1024
	ds_read_b128 v[194:197], v46 offset:2048
	ds_read_b128 v[198:201], v46 offset:3072
	ds_read_b128 v[202:205], v46 offset:4096
	ds_read_b128 v[206:209], v46 offset:5120
	ds_read_b128 v[210:213], v46 offset:6144
	ds_read_b128 v[214:217], v46 offset:7168
	global_load_lds_dwordx4 v[54:55], off
	v_lshl_add_u64 v[54:55], v[42:43], 0, s[6:7]
	s_mov_b32 m0, s23
	s_nop 0
	global_load_lds_dwordx4 v[54:55], off
	s_waitcnt vmcnt(8)
	s_waitcnt lgkmcnt(0)
	s_barrier
	s_setprio 1
	s_waitcnt lgkmcnt(0)
	v_mfma_f32_16x16x32_bf16 v[140:143], v[50:53], v[186:189], v[140:143]
	v_mfma_f32_16x16x32_bf16 v[136:139], v[160:163], v[186:189], v[136:139]
	v_mfma_f32_16x16x32_bf16 v[124:127], v[50:53], v[194:197], v[124:127]
	v_mfma_f32_16x16x32_bf16 v[120:123], v[160:163], v[194:197], v[120:123]
	v_mfma_f32_16x16x32_bf16 v[108:111], v[50:53], v[202:205], v[108:111]
	v_mfma_f32_16x16x32_bf16 v[104:107], v[160:163], v[202:205], v[104:107]
	v_mfma_f32_16x16x32_bf16 v[92:95], v[50:53], v[210:213], v[92:95]
	v_mfma_f32_16x16x32_bf16 v[88:91], v[160:163], v[210:213], v[88:91]
	v_mfma_f32_16x16x32_bf16 v[140:143], v[156:159], v[190:193], v[140:143]
	v_mfma_f32_16x16x32_bf16 v[136:139], v[164:167], v[190:193], v[136:139]
	v_mfma_f32_16x16x32_bf16 v[124:127], v[156:159], v[198:201], v[124:127]
	v_mfma_f32_16x16x32_bf16 v[120:123], v[164:167], v[198:201], v[120:123]
	v_mfma_f32_16x16x32_bf16 v[108:111], v[156:159], v[206:209], v[108:111]
	v_mfma_f32_16x16x32_bf16 v[104:107], v[164:167], v[206:209], v[104:107]
	v_mfma_f32_16x16x32_bf16 v[92:95], v[156:159], v[214:217], v[92:95]
	v_mfma_f32_16x16x32_bf16 v[88:91], v[164:167], v[214:217], v[88:91]
	s_setprio 0
	s_setprio 1
	v_mfma_f32_16x16x32_bf16 v[132:135], v[168:171], v[186:189], v[132:135]
	v_mfma_f32_16x16x32_bf16 v[128:131], v[176:179], v[186:189], v[128:131]
	v_mfma_f32_16x16x32_bf16 v[116:119], v[168:171], v[194:197], v[116:119]
	v_mfma_f32_16x16x32_bf16 v[112:115], v[176:179], v[194:197], v[112:115]
	v_mfma_f32_16x16x32_bf16 v[100:103], v[168:171], v[202:205], v[100:103]
	v_mfma_f32_16x16x32_bf16 v[96:99], v[176:179], v[202:205], v[96:99]
	v_mfma_f32_16x16x32_bf16 v[84:87], v[168:171], v[210:213], v[84:87]
	v_mfma_f32_16x16x32_bf16 v[80:83], v[176:179], v[210:213], v[80:83]
	v_mfma_f32_16x16x32_bf16 v[132:135], v[172:175], v[190:193], v[132:135]
	v_mfma_f32_16x16x32_bf16 v[128:131], v[180:183], v[190:193], v[128:131]
	v_mfma_f32_16x16x32_bf16 v[116:119], v[172:175], v[198:201], v[116:119]
	v_mfma_f32_16x16x32_bf16 v[112:115], v[180:183], v[198:201], v[112:115]
	v_mfma_f32_16x16x32_bf16 v[100:103], v[172:175], v[206:209], v[100:103]
	v_mfma_f32_16x16x32_bf16 v[96:99], v[180:183], v[206:209], v[96:99]
	v_mfma_f32_16x16x32_bf16 v[84:87], v[172:175], v[214:217], v[84:87]
	v_mfma_f32_16x16x32_bf16 v[80:83], v[180:183], v[214:217], v[80:83]
	s_setprio 0
	s_barrier
	s_mov_b32 m0, s40
	v_lshl_add_u64 v[218:219], s[8:9], 0, v[150:151]
	s_add_u32 s48, s8, 0x80000
	ds_read_b128 v[186:189], v46 offset:16384
	ds_read_b128 v[190:193], v46 offset:17408
	ds_read_b128 v[194:197], v46 offset:18432
	ds_read_b128 v[198:201], v46 offset:19456
	ds_read_b128 v[202:205], v46 offset:20480
	ds_read_b128 v[206:209], v46 offset:21504
	ds_read_b128 v[210:213], v46 offset:22528
	ds_read_b128 v[214:217], v46 offset:23552
	global_load_lds_dwordx4 v[218:219], off
	v_lshl_add_u64 v[220:221], s[8:9], 0, v[154:155]
	s_mov_b32 m0, s41
	s_addc_u32 s49, s9, 0
	global_load_lds_dwordx4 v[220:221], off
	v_lshl_add_u64 v[54:55], s[48:49], 0, v[150:151]
	s_mov_b32 m0, s42
	v_lshl_add_u64 v[222:223], s[10:11], 0, v[148:149]
	global_load_lds_dwordx4 v[54:55], off
	v_lshl_add_u64 v[54:55], s[48:49], 0, v[154:155]
	s_mov_b32 m0, s43
	v_lshl_add_u64 v[224:225], s[10:11], 0, v[152:153]
	global_load_lds_dwordx4 v[54:55], off
	s_mov_b32 m0, s12
	s_nop 0
	global_load_lds_dwordx4 v[222:223], off
	s_mov_b32 m0, s14
	s_nop 0
	global_load_lds_dwordx4 v[224:225], off
	s_waitcnt vmcnt(8)
	s_waitcnt lgkmcnt(0)
	s_barrier
	s_setprio 1
	s_waitcnt lgkmcnt(0)
	v_mfma_f32_16x16x32_bf16 v[76:79], v[50:53], v[186:189], v[76:79]
	v_mfma_f32_16x16x32_bf16 v[72:75], v[160:163], v[186:189], v[72:75]
	v_mfma_f32_16x16x32_bf16 v[60:63], v[50:53], v[194:197], v[60:63]
	v_mfma_f32_16x16x32_bf16 v[54:57], v[160:163], v[194:197], v[56:59]
	v_mfma_f32_16x16x32_bf16 v[28:31], v[50:53], v[202:205], v[28:31]
	v_mfma_f32_16x16x32_bf16 v[24:27], v[160:163], v[202:205], v[24:27]
	v_mfma_f32_16x16x32_bf16 v[12:15], v[50:53], v[210:213], v[12:15]
	v_mfma_f32_16x16x32_bf16 v[8:11], v[160:163], v[210:213], v[8:11]
	v_mfma_f32_16x16x32_bf16 v[76:79], v[156:159], v[190:193], v[76:79]
	v_mfma_f32_16x16x32_bf16 v[72:75], v[164:167], v[190:193], v[72:75]
	v_mfma_f32_16x16x32_bf16 v[60:63], v[156:159], v[198:201], v[60:63]
	v_mfma_f32_16x16x32_bf16 v[54:57], v[164:167], v[198:201], v[54:57]
	v_mfma_f32_16x16x32_bf16 v[28:31], v[156:159], v[206:209], v[28:31]
	v_mfma_f32_16x16x32_bf16 v[24:27], v[164:167], v[206:209], v[24:27]
	v_mfma_f32_16x16x32_bf16 v[12:15], v[156:159], v[214:217], v[12:15]
	v_mfma_f32_16x16x32_bf16 v[8:11], v[164:167], v[214:217], v[8:11]
	s_setprio 0
	s_setprio 1
	v_mfma_f32_16x16x32_bf16 v[64:67], v[176:179], v[186:189], v[64:67]
	v_mfma_f32_16x16x32_bf16 v[36:39], v[168:171], v[194:197], v[36:39]
	v_mfma_f32_16x16x32_bf16 v[32:35], v[176:179], v[194:197], v[32:35]
	v_mfma_f32_16x16x32_bf16 v[20:23], v[168:171], v[202:205], v[20:23]
	v_mfma_f32_16x16x32_bf16 v[16:19], v[176:179], v[202:205], v[16:19]
	v_mfma_f32_16x16x32_bf16 v[4:7], v[168:171], v[210:213], v[4:7]
	v_mfma_f32_16x16x32_bf16 v[0:3], v[176:179], v[210:213], v[0:3]
	v_mfma_f32_16x16x32_bf16 v[50:53], v[168:171], v[186:189], v[68:71]
	v_mfma_f32_16x16x32_bf16 v[64:67], v[180:183], v[190:193], v[64:67]
	v_mfma_f32_16x16x32_bf16 v[36:39], v[172:175], v[198:201], v[36:39]
	v_mfma_f32_16x16x32_bf16 v[32:35], v[180:183], v[198:201], v[32:35]
	v_mfma_f32_16x16x32_bf16 v[20:23], v[172:175], v[206:209], v[20:23]
	v_mfma_f32_16x16x32_bf16 v[16:19], v[180:183], v[206:209], v[16:19]
	v_mfma_f32_16x16x32_bf16 v[4:7], v[172:175], v[214:217], v[4:7]
	v_mfma_f32_16x16x32_bf16 v[0:3], v[180:183], v[214:217], v[0:3]
	v_mfma_f32_16x16x32_bf16 v[50:53], v[172:175], v[190:193], v[50:53]
	s_setprio 0
	s_barrier
	ds_read_b128 v[68:71], v47
	ds_read_b128 v[156:159], v47 offset:1024
	ds_read_b128 v[160:163], v47 offset:2048
	ds_read_b128 v[164:167], v47 offset:3072
	ds_read_b128 v[168:171], v48
	ds_read_b128 v[172:175], v48 offset:1024
	ds_read_b128 v[176:179], v48 offset:2048
	ds_read_b128 v[180:183], v48 offset:3072
	s_add_u32 s10, s10, 0x80000
	s_addc_u32 s11, s11, 0
	s_mov_b32 m0, s15
	v_lshl_add_u64 v[58:59], s[10:11], 0, v[148:149]
	ds_read_b128 v[186:189], v46 offset:32768
	ds_read_b128 v[190:193], v46 offset:33792
	ds_read_b128 v[194:197], v46 offset:34816
	ds_read_b128 v[198:201], v46 offset:35840
	ds_read_b128 v[202:205], v46 offset:36864
	ds_read_b128 v[206:209], v46 offset:37888
	ds_read_b128 v[210:213], v46 offset:38912
	ds_read_b128 v[214:217], v46 offset:39936
	global_load_lds_dwordx4 v[58:59], off
	v_lshl_add_u64 v[58:59], s[10:11], 0, v[152:153]
	s_mov_b32 m0, s16
	s_nop 0
	global_load_lds_dwordx4 v[58:59], off
	s_waitcnt vmcnt(8)
	s_waitcnt lgkmcnt(0)
	s_barrier
	s_setprio 1
	s_waitcnt lgkmcnt(0)
	v_mfma_f32_16x16x32_bf16 v[140:143], v[68:71], v[186:189], v[140:143]
	v_mfma_f32_16x16x32_bf16 v[136:139], v[160:163], v[186:189], v[136:139]
	v_mfma_f32_16x16x32_bf16 v[124:127], v[68:71], v[194:197], v[124:127]
	v_mfma_f32_16x16x32_bf16 v[120:123], v[160:163], v[194:197], v[120:123]
	v_mfma_f32_16x16x32_bf16 v[108:111], v[68:71], v[202:205], v[108:111]
	v_mfma_f32_16x16x32_bf16 v[104:107], v[160:163], v[202:205], v[104:107]
	v_mfma_f32_16x16x32_bf16 v[92:95], v[68:71], v[210:213], v[92:95]
	v_mfma_f32_16x16x32_bf16 v[88:91], v[160:163], v[210:213], v[88:91]
	v_mfma_f32_16x16x32_bf16 v[140:143], v[156:159], v[190:193], v[140:143]
	v_mfma_f32_16x16x32_bf16 v[136:139], v[164:167], v[190:193], v[136:139]
	v_mfma_f32_16x16x32_bf16 v[124:127], v[156:159], v[198:201], v[124:127]
	v_mfma_f32_16x16x32_bf16 v[120:123], v[164:167], v[198:201], v[120:123]
	v_mfma_f32_16x16x32_bf16 v[108:111], v[156:159], v[206:209], v[108:111]
	v_mfma_f32_16x16x32_bf16 v[104:107], v[164:167], v[206:209], v[104:107]
	v_mfma_f32_16x16x32_bf16 v[92:95], v[156:159], v[214:217], v[92:95]
	v_mfma_f32_16x16x32_bf16 v[88:91], v[164:167], v[214:217], v[88:91]
	s_setprio 0
	s_setprio 1
	v_mfma_f32_16x16x32_bf16 v[132:135], v[168:171], v[186:189], v[132:135]
	v_mfma_f32_16x16x32_bf16 v[128:131], v[176:179], v[186:189], v[128:131]
	v_mfma_f32_16x16x32_bf16 v[116:119], v[168:171], v[194:197], v[116:119]
	v_mfma_f32_16x16x32_bf16 v[112:115], v[176:179], v[194:197], v[112:115]
	v_mfma_f32_16x16x32_bf16 v[100:103], v[168:171], v[202:205], v[100:103]
	v_mfma_f32_16x16x32_bf16 v[96:99], v[176:179], v[202:205], v[96:99]
	v_mfma_f32_16x16x32_bf16 v[84:87], v[168:171], v[210:213], v[84:87]
	v_mfma_f32_16x16x32_bf16 v[80:83], v[176:179], v[210:213], v[80:83]
	v_mfma_f32_16x16x32_bf16 v[132:135], v[172:175], v[190:193], v[132:135]
	v_mfma_f32_16x16x32_bf16 v[128:131], v[180:183], v[190:193], v[128:131]
	v_mfma_f32_16x16x32_bf16 v[116:119], v[172:175], v[198:201], v[116:119]
	v_mfma_f32_16x16x32_bf16 v[112:115], v[180:183], v[198:201], v[112:115]
	v_mfma_f32_16x16x32_bf16 v[100:103], v[172:175], v[206:209], v[100:103]
	v_mfma_f32_16x16x32_bf16 v[96:99], v[180:183], v[206:209], v[96:99]
	v_mfma_f32_16x16x32_bf16 v[84:87], v[172:175], v[214:217], v[84:87]
	v_mfma_f32_16x16x32_bf16 v[80:83], v[180:183], v[214:217], v[80:83]
	s_setprio 0
	s_barrier
	s_mov_b32 m0, s44
	v_lshl_add_u64 v[58:59], v[218:219], 0, s[4:5]
	s_add_u32 s8, s8, 0x80080
	ds_read_b128 v[186:189], v46 offset:49152
	ds_read_b128 v[190:193], v46 offset:50176
	ds_read_b128 v[194:197], v46 offset:51200
	ds_read_b128 v[198:201], v46 offset:52224
	ds_read_b128 v[202:205], v46 offset:53248
	ds_read_b128 v[206:209], v46 offset:54272
	ds_read_b128 v[210:213], v46 offset:55296
	ds_read_b128 v[214:217], v46 offset:56320
	global_load_lds_dwordx4 v[58:59], off
	v_lshl_add_u64 v[58:59], v[220:221], 0, s[4:5]
	s_mov_b32 m0, s45
	s_addc_u32 s9, s9, 0
	global_load_lds_dwordx4 v[58:59], off
	v_lshl_add_u64 v[58:59], s[8:9], 0, v[150:151]
	s_mov_b32 m0, s46
	s_nop 0
	global_load_lds_dwordx4 v[58:59], off
	v_lshl_add_u64 v[58:59], s[8:9], 0, v[154:155]
	s_mov_b32 m0, s47
	s_nop 0
	global_load_lds_dwordx4 v[58:59], off
	v_lshl_add_u64 v[58:59], v[222:223], 0, s[4:5]
	s_mov_b32 m0, s17
	s_nop 0
	global_load_lds_dwordx4 v[58:59], off
	v_lshl_add_u64 v[58:59], v[224:225], 0, s[4:5]
	s_mov_b32 m0, s18
	s_nop 0
	global_load_lds_dwordx4 v[58:59], off
	s_waitcnt vmcnt(8)
	s_waitcnt lgkmcnt(0)
	s_barrier
	s_setprio 1
	s_waitcnt lgkmcnt(0)
	v_mfma_f32_16x16x32_bf16 v[76:79], v[68:71], v[186:189], v[76:79]
	v_mfma_f32_16x16x32_bf16 v[72:75], v[160:163], v[186:189], v[72:75]
	v_mfma_f32_16x16x32_bf16 v[58:61], v[68:71], v[194:197], v[60:63]
	v_mfma_f32_16x16x32_bf16 v[54:57], v[160:163], v[194:197], v[54:57]
	v_mfma_f32_16x16x32_bf16 v[28:31], v[68:71], v[202:205], v[28:31]
	v_mfma_f32_16x16x32_bf16 v[24:27], v[160:163], v[202:205], v[24:27]
	v_mfma_f32_16x16x32_bf16 v[12:15], v[68:71], v[210:213], v[12:15]
	v_mfma_f32_16x16x32_bf16 v[8:11], v[160:163], v[210:213], v[8:11]
	v_mfma_f32_16x16x32_bf16 v[76:79], v[156:159], v[190:193], v[76:79]
	v_mfma_f32_16x16x32_bf16 v[72:75], v[164:167], v[190:193], v[72:75]
	v_mfma_f32_16x16x32_bf16 v[60:63], v[156:159], v[198:201], v[58:61]
	v_mfma_f32_16x16x32_bf16 v[56:59], v[164:167], v[198:201], v[54:57]
	v_mfma_f32_16x16x32_bf16 v[28:31], v[156:159], v[206:209], v[28:31]
	v_mfma_f32_16x16x32_bf16 v[24:27], v[164:167], v[206:209], v[24:27]
	v_mfma_f32_16x16x32_bf16 v[12:15], v[156:159], v[214:217], v[12:15]
	v_mfma_f32_16x16x32_bf16 v[8:11], v[164:167], v[214:217], v[8:11]
	s_setprio 0
	s_setprio 1
	v_mfma_f32_16x16x32_bf16 v[50:53], v[168:171], v[186:189], v[50:53]
	v_mfma_f32_16x16x32_bf16 v[68:71], v[172:175], v[190:193], v[50:53]
	v_mfma_f32_16x16x32_bf16 v[50:53], v[176:179], v[186:189], v[64:67]
	v_mfma_f32_16x16x32_bf16 v[36:39], v[168:171], v[194:197], v[36:39]
	v_mfma_f32_16x16x32_bf16 v[32:35], v[176:179], v[194:197], v[32:35]
	v_mfma_f32_16x16x32_bf16 v[20:23], v[168:171], v[202:205], v[20:23]
	v_mfma_f32_16x16x32_bf16 v[16:19], v[176:179], v[202:205], v[16:19]
	v_mfma_f32_16x16x32_bf16 v[4:7], v[168:171], v[210:213], v[4:7]
	v_mfma_f32_16x16x32_bf16 v[0:3], v[176:179], v[210:213], v[0:3]
	v_mfma_f32_16x16x32_bf16 v[64:67], v[180:183], v[190:193], v[50:53]
	v_mfma_f32_16x16x32_bf16 v[36:39], v[172:175], v[198:201], v[36:39]
	v_mfma_f32_16x16x32_bf16 v[32:35], v[180:183], v[198:201], v[32:35]
	v_mfma_f32_16x16x32_bf16 v[20:23], v[172:175], v[206:209], v[20:23]
	v_mfma_f32_16x16x32_bf16 v[16:19], v[180:183], v[206:209], v[16:19]
	v_mfma_f32_16x16x32_bf16 v[4:7], v[172:175], v[214:217], v[4:7]
	v_mfma_f32_16x16x32_bf16 v[0:3], v[180:183], v[214:217], v[0:3]
	s_setprio 0
	s_barrier
	s_add_i32 s21, s21, 2
	s_add_u32 s6, s6, 0x100
	s_addc_u32 s7, s7, 0
	s_cmp_lt_u32 s21, 30
	s_cbranch_scc1 .LBB0_338
	s_andn2_b64 vcc, exec, s[38:39]
	s_cbranch_vccnz .LBB0_341
	s_barrier

.LBB0_651:
	s_add_u32 s14, s94, 0xf200000
	s_addc_u32 s15, s95, 0
	s_add_u32 s16, s94, 0x12000000
	s_mov_b64 s[18:19], 0x80
	s_addc_u32 s17, s95, 0
	s_bfe_u32 s43, s33, 0x20006
	s_add_i32 m0, s39, 0x18000
	v_lshl_add_u64 v[6:7], v[6:7], 0, s[18:19]
	s_lshl_b32 s44, s3, 6
	s_lshl_b32 s45, s43, 5
	global_load_lds_dwordx4 v[6:7], off
	v_lshl_add_u64 v[4:5], v[4:5], 0, s[18:19]
	s_add_i32 m0, s39, 0x1a000
	s_add_i32 s46, s39, 0x8000
	s_add_i32 s47, s39, 0xa000
	global_load_lds_dwordx4 v[4:5], off
	v_lshl_add_u64 v[0:1], v[0:1], 0, s[18:19]
	s_mov_b32 m0, s46
	s_add_u32 s20, s8, 0x80080
	global_load_lds_dwordx4 v[0:1], off
	v_lshl_add_u64 v[0:1], v[2:3], 0, s[18:19]
	s_mov_b32 m0, s47
	s_addc_u32 s21, s9, 0
	global_load_lds_dwordx4 v[0:1], off
	s_add_i32 m0, s39, 0x1c000
	v_lshl_add_u64 v[0:1], s[20:21], 0, v[188:189]
	global_load_lds_dwordx4 v[0:1], off
	v_lshl_add_u64 v[0:1], s[20:21], 0, v[184:185]
	s_add_i32 m0, s39, 0x1e000
	v_and_b32_e32 v229, 15, v9
	global_load_lds_dwordx4 v[0:1], off
	v_and_b32_e32 v0, 48, v9
	v_and_b32_e32 v1, 0xfffffc00, v11
	v_lshlrev_b32_e32 v3, 2, v9
	s_cmpk_lt_u32 s33, 0x100
	v_lshl_add_u32 v2, s3, 13, v1
	v_lshl_or_b32 v0, v229, 6, v0
	v_and_b32_e32 v3, 32, v3
	v_lshl_add_u32 v1, s43, 12, v1
	s_cselect_b64 s[22:23], -1, 0
	s_lshl_b32 s0, s0, 20
	v_bitop3_b32 v2, v0, v2, v3 bitop3:0xde
	v_bitop3_b32 v3, v0, v1, v3 bitop3:0xde
	s_lshl_b32 s1, s1, 24
	v_lshlrev_b32_e32 v0, 15, v13
	s_or_b32 s0, s2, s0
	v_and_b32_e32 v0, 0xffff0000, v0
	s_add_u32 s0, s94, s0
	v_lshl_add_u32 v0, v14, 12, v0
	v_and_b32_e32 v1, 1, v13
	s_addc_u32 s2, s95, 0
	v_lshl_or_b32 v0, v1, 6, v0
	s_add_u32 s0, s0, s1
	v_lshl_add_u32 v0, v15, 1, v0
	v_mov_b32_e32 v1, v189
	s_addc_u32 s1, s2, 0
	v_lshl_add_u64 v[192:193], s[0:1], 0, v[0:1]
	v_lshlrev_b32_e32 v0, 15, v8
	v_and_b32_e32 v0, 0xffff0000, v0
	v_lshl_add_u32 v0, v10, 12, v0
	v_and_b32_e32 v1, 1, v8
	v_lshl_or_b32 v0, v1, 6, v0
	s_waitcnt vmcnt(6)
	v_lshl_add_u32 v0, v12, 1, v0
	v_mov_b32_e32 v1, v189
	s_add_i32 s50, 0, 0x10000
	s_add_i32 s52, 0, 0x14000
	v_lshl_add_u64 v[194:195], s[0:1], 0, v[0:1]
	v_add_u32_e32 v230, s50, v3
	v_add_u32_e32 v231, s52, v3
	v_mbcnt_lo_u32_b32 v0, -1, 0
	s_add_i32 s50, s50, s37
	s_add_i32 s52, s52, s37
	s_add_i32 s55, 0, 0x18000
	s_add_i32 s54, 0, 0x1c000
	v_ashrrev_i32_e32 v228, 4, v9
	s_mov_b32 s21, 0
	v_add_u32_e32 v232, 0, v2
	s_mov_b64 s[24:25], 0x1387ff80
	s_lshr_b32 s84, s88, 2
	s_mul_i32 s85, s84, 0x3000
	s_add_i32 s85, s85, s39
	s_mul_i32 s96, s84, 0x60000
	s_mov_b32 s97, 0
	s_sub_u32 s86, s24, 0x80000
	s_subb_u32 s87, s25, 0
	s_add_u32 s86, s86, s96
	s_addc_u32 s87, s87, 0
	v_mbcnt_hi_u32_b32 v233, -1, v0
	s_add_i32 s48, s39, 0xc000
	s_add_i32 s49, s39, 0xe000
	s_add_i32 s51, s50, 0x2000
	s_add_i32 s53, s52, 0x2000
	v_add_u32_e32 v234, s55, v3
	v_add_u32_e32 v235, s54, v3
	s_add_i32 s55, s55, s37
	s_mov_b32 s56, 0
	s_barrier
	s_lshr_b32 s100, s88, 2
	s_cmp_lg_u32 s100, 1
	s_cbranch_scc1 .Lpro_lag4
	s_barrier

.LBB0_773:
.LBB0_774:
	s_add_i32 s0, 0, 0x23f94
	s_waitcnt vmcnt(1)
	v_mov_b32_e32 v0, s0
	v_mbcnt_lo_u32_b32 v24, -1, 0
	v_mbcnt_hi_u32_b32 v24, -1, v24
	ds_read_b32 v0, v0
	s_waitcnt lgkmcnt(0)
	v_readfirstlane_b32 s4, v0
	s_ashr_i32 s19, s4, 3
	s_cmp_gt_i32 s19, 31
	s_cbranch_scc1 .LBB0_792
	s_and_b32 s16, s4, 7
	s_and_b32 s0, s33, 0xffffffc0
	v_add_u32_e32 v25, s0, v24
	s_and_b32 s0, s19, 3
	s_lshl_b32 s1, s16, 2
	s_or_b32 s42, s1, s0
	s_movk_i32 s0, 0x100
	v_cmp_gt_i32_e64 s[2:3], s0, v25
	s_and_saveexec_b64 s[0:1], s[2:3]
	s_cbranch_execz .LBB0_777
	v_lshl_add_u32 v0, s42, 8, v25
	v_ashrrev_i32_e32 v1, 31, v0
	v_lshlrev_b64 v[0:1], 8, v[0:1]
	v_lshl_add_u64 v[0:1], s[94:95], 0, v[0:1]
	s_mov_b64 s[8:9], 0x12000000
	v_lshl_add_u64 v[10:11], v[0:1], 0, s[8:9]
	v_add_co_u32_e32 v0, vcc, 0x12000000, v0
	global_load_dwordx4 v[248:251], v[10:11], off offset:32
	global_load_dwordx4 v[244:247], v[10:11], off offset:16
	global_load_dwordx4 v[240:243], v[10:11], off offset:96
	global_load_dwordx4 v[236:239], v[10:11], off offset:80
	v_addc_co_u32_e32 v1, vcc, 0, v1, vcc
	global_load_dwordx4 v[232:235], v[0:1], off
	global_load_dwordx4 v[228:231], v[10:11], off offset:64
	global_load_dwordx4 v[224:227], v[10:11], off offset:48
	global_load_dwordx4 v[220:223], v[10:11], off offset:112

.LBB0_779:
	s_mov_b64 s[12:13], 0x80
	s_add_i32 m0, s47, 0x18000
	v_lshl_add_u64 v[22:23], v[22:23], 0, s[12:13]
	global_load_lds_dwordx4 v[22:23], off
	v_lshl_add_u64 v[20:21], v[20:21], 0, s[12:13]
	s_add_i32 m0, s47, 0x1a000
	s_add_i32 s51, s47, 0x8000
	s_add_i32 s52, s47, 0xa000
	global_load_lds_dwordx4 v[20:21], off
	v_lshl_add_u64 v[16:17], v[16:17], 0, s[12:13]
	s_mov_b32 m0, s51
	s_add_u32 s14, s10, 0x80080
	global_load_lds_dwordx4 v[16:17], off
	v_lshl_add_u64 v[16:17], v[18:19], 0, s[12:13]
	s_mov_b32 m0, s52
	s_addc_u32 s15, s11, 0
	global_load_lds_dwordx4 v[16:17], off
	s_add_i32 m0, s47, 0x1c000
	v_lshl_add_u64 v[16:17], s[14:15], 0, v[130:131]
	global_load_lds_dwordx4 v[16:17], off
	v_lshl_add_u64 v[16:17], s[14:15], 0, v[134:135]
	s_add_i32 m0, s47, 0x1e000
	s_nop 0
	global_load_lds_dwordx4 v[16:17], off
	s_waitcnt vmcnt(6)
	s_barrier
	s_and_saveexec_b64 s[14:15], s[2:3]
	s_cbranch_execz .LBB0_781
	v_pk_add_f32 v[0:1], v[250:251], v[242:243]
	v_pk_add_f32 v[8:9], v[246:247], v[238:239]
	v_pk_add_f32 v[10:11], v[244:245], v[236:237]
	v_pk_add_f32 v[4:5], v[248:249], v[240:241]
	v_pk_add_f32 v[12:13], v[234:235], v[230:231]
	v_pk_add_f32 v[14:15], v[232:233], v[228:229]
	v_pk_add_f32 v[2:3], v[226:227], v[222:223]
	v_pk_add_f32 v[6:7], v[224:225], v[220:221]
	v_pk_add_f32 v[10:11], v[10:11], v[14:15]
	v_pk_add_f32 v[8:9], v[8:9], v[12:13]
	v_pk_add_f32 v[4:5], v[6:7], v[4:5]
	v_pk_add_f32 v[0:1], v[2:3], v[0:1]
	v_pk_add_f32 v[2:3], v[4:5], v[10:11]
	v_pk_add_f32 v[0:1], v[0:1], v[8:9]
	s_nop 0
	v_pk_mov_b32 v[4:5], v[2:3], v[0:1] op_sel:[1,0]
	v_mov_b32_e32 v3, v1
	v_pk_add_f32 v[0:1], v[4:5], v[2:3]
	s_nop 0
	v_add_f32_e32 v0, v0, v1
	v_mov_b32_e32 v1, 0x358637bd
	v_fmac_f32_e32 v1, 0x3a000000, v0
	v_rsq_f32_e32 v0, v1
	v_lshl_add_u32 v1, v25, 2, 0
	v_add_u32_e32 v1, 0x20000, v1
	ds_write_b32 v1, v0
.LBB0_781:
	s_or_b64 exec, exec, s[14:15]
	s_mul_i32 s2, s16, 0x1400000
	s_add_u32 s2, s94, s2
	s_addc_u32 s3, s95, 0
	s_lshl_b32 s14, s16, 22
	s_sub_u32 s14, 0, s14
	s_subb_u32 s15, 0, 0
	s_add_u32 s2, s2, s14
	s_addc_u32 s3, s3, s15
	s_add_u32 s2, s2, 0x13c00000
	s_addc_u32 s3, s3, 0
	v_ashrrev_i32_e32 v0, 6, v24
	s_lshl_b32 s14, s17, 13
	v_lshl_add_u32 v2, v0, 10, s14
	s_lshl_b32 s14, s88, 5
	s_and_b32 s55, s14, 0x60
	v_and_b32_e32 v146, 15, v24
	v_and_b32_e32 v1, 48, v24
	v_lshlrev_b32_e32 v3, 2, v24
	s_lshr_b32 s14, s55, 3
	v_lshl_or_b32 v1, v146, 6, v1
	v_and_b32_e32 v3, 32, v3
	v_add_lshl_u32 v0, v0, s14, 10
	v_bitop3_b32 v2, v1, v2, v3 bitop3:0xde
	v_bitop3_b32 v0, v1, v0, v3 bitop3:0xde
	v_lshlrev_b32_e32 v1, 15, v26
	v_and_b32_e32 v1, 0xffff0000, v1
	v_lshl_add_u32 v1, v27, 12, v1
	v_and_b32_e32 v3, 1, v26
	v_lshl_or_b32 v1, v3, 6, v1
	s_lshl_b32 s54, s17, 6
	v_lshl_add_u32 v136, v28, 1, v1
	v_lshlrev_b32_e32 v1, 15, v29
	s_cmpk_lt_u32 s33, 0x100
	v_and_b32_e32 v1, 0xffff0000, v1
	s_cselect_b64 s[14:15], -1, 0
	s_lshl_b32 s16, s17, 8
	v_lshl_add_u32 v1, v30, 12, v1
	v_and_b32_e32 v3, 1, v29
	s_add_i32 s57, s16, 0
	v_mov_b32_e32 v137, 0
	v_lshl_or_b32 v1, v3, 6, v1
	s_add_i32 s59, 0, 0x10000
	s_add_i32 s60, 0, 0x14000
	s_add_i32 s61, 0, 0x18000
	s_add_i32 s62, 0, 0x1c000
	s_mov_b32 s53, 0
	v_ashrrev_i32_e32 v147, 4, v24
	s_mov_b32 s56, 0x20000
	s_add_i32 s57, s57, 0x20000
	v_lshl_add_u32 v138, v31, 1, v1
	v_mov_b32_e32 v139, v137
	s_mov_b32 s58, 0x10000
	v_add_u32_e32 v148, s59, v0
	v_add_u32_e32 v149, s60, v0
	v_add_u32_e32 v150, 0, v2
	s_mov_b64 s[16:17], 0x80000
	v_add_u32_e32 v151, s61, v0
	v_add_u32_e32 v152, s62, v0
	s_mov_b32 s18, 0x3d8293ee
	s_mov_b64 s[20:21], 0x10000
	s_mov_b64 s[22:23], 0x20000
	s_mov_b64 s[24:25], 0x30000
	s_mov_b32 s63, 0x30000
	s_mov_b32 s64, 0x80000
	s_mov_b64 s[26:27], 0x90000
	s_mov_b32 s65, 0x90000
	s_mov_b64 s[28:29], 0xa0000
	s_mov_b32 s66, 0xa0000
	s_mov_b64 s[30:31], 0xb0000
	s_mov_b32 s67, 0xb0000
	s_lshr_b32 s84, s88, 2
	s_mul_i32 s85, s84, 0x3000
	s_add_i32 s85, s85, s47
	s_mul_i32 s86, s84, 0x60000
	v_add_u32_e32 v222, s86, v136
	s_lshr_b32 s100, s88, 2
	s_cmp_lg_u32 s100, 1
	s_cbranch_scc1 .Lpro_lag5
	s_barrier

.LBB0_950:
	s_add_u32 s14, s94, 0xf200000
	s_addc_u32 s15, s95, 0
	s_add_u32 s16, s94, 0x12000000
	s_mov_b64 s[18:19], 0x80
	s_addc_u32 s17, s95, 0
	s_bfe_u32 s43, s33, 0x20006
	s_add_i32 m0, s39, 0x18000
	v_lshl_add_u64 v[6:7], v[6:7], 0, s[18:19]
	s_lshl_b32 s44, s3, 6
	s_lshl_b32 s45, s43, 5
	global_load_lds_dwordx4 v[6:7], off
	v_lshl_add_u64 v[4:5], v[4:5], 0, s[18:19]
	s_add_i32 m0, s39, 0x1a000
	s_add_i32 s46, s39, 0x8000
	s_add_i32 s47, s39, 0xa000
	global_load_lds_dwordx4 v[4:5], off
	v_lshl_add_u64 v[0:1], v[0:1], 0, s[18:19]
	s_mov_b32 m0, s46
	s_add_u32 s20, s8, 0x80080
	global_load_lds_dwordx4 v[0:1], off
	v_lshl_add_u64 v[0:1], v[2:3], 0, s[18:19]
	s_mov_b32 m0, s47
	s_addc_u32 s21, s9, 0
	global_load_lds_dwordx4 v[0:1], off
	s_add_i32 m0, s39, 0x1c000
	v_lshl_add_u64 v[0:1], s[20:21], 0, v[188:189]
	global_load_lds_dwordx4 v[0:1], off
	v_lshl_add_u64 v[0:1], s[20:21], 0, v[184:185]
	s_add_i32 m0, s39, 0x1e000
	v_and_b32_e32 v229, 15, v9
	global_load_lds_dwordx4 v[0:1], off
	v_and_b32_e32 v0, 48, v9
	v_and_b32_e32 v1, 0xfffffc00, v11
	v_lshlrev_b32_e32 v3, 2, v9
	s_cmpk_lt_u32 s33, 0x100
	v_lshl_add_u32 v2, s3, 13, v1
	v_lshl_or_b32 v0, v229, 6, v0
	v_and_b32_e32 v3, 32, v3
	v_lshl_add_u32 v1, s43, 12, v1
	s_cselect_b64 s[22:23], -1, 0
	s_lshl_b32 s0, s0, 20
	v_bitop3_b32 v2, v0, v2, v3 bitop3:0xde
	v_bitop3_b32 v3, v0, v1, v3 bitop3:0xde
	s_lshl_b32 s1, s1, 24
	v_lshlrev_b32_e32 v0, 15, v13
	s_or_b32 s0, s2, s0
	v_and_b32_e32 v0, 0xffff0000, v0
	s_add_u32 s0, s94, s0
	v_lshl_add_u32 v0, v14, 12, v0
	v_and_b32_e32 v1, 1, v13
	s_addc_u32 s2, s95, 0
	v_lshl_or_b32 v0, v1, 6, v0
	s_add_u32 s0, s0, s1
	v_lshl_add_u32 v0, v15, 1, v0
	v_mov_b32_e32 v1, v189
	s_addc_u32 s1, s2, 0
	v_lshl_add_u64 v[192:193], s[0:1], 0, v[0:1]
	v_lshlrev_b32_e32 v0, 15, v8
	v_and_b32_e32 v0, 0xffff0000, v0
	v_lshl_add_u32 v0, v10, 12, v0
	v_and_b32_e32 v1, 1, v8
	v_lshl_or_b32 v0, v1, 6, v0
	s_waitcnt vmcnt(6)
	v_lshl_add_u32 v0, v12, 1, v0
	v_mov_b32_e32 v1, v189
	s_add_i32 s50, 0, 0x10000
	s_add_i32 s52, 0, 0x14000
	v_lshl_add_u64 v[194:195], s[0:1], 0, v[0:1]
	v_add_u32_e32 v230, s50, v3
	v_add_u32_e32 v231, s52, v3
	v_mbcnt_lo_u32_b32 v0, -1, 0
	s_add_i32 s50, s50, s37
	s_add_i32 s52, s52, s37
	s_add_i32 s55, 0, 0x18000
	s_add_i32 s54, 0, 0x1c000
	v_ashrrev_i32_e32 v228, 4, v9
	s_mov_b32 s21, 0
	v_add_u32_e32 v232, 0, v2
	s_mov_b64 s[24:25], 0x1407ff80
	s_lshr_b32 s84, s88, 2
	s_mul_i32 s85, s84, 0x3000
	s_add_i32 s85, s85, s39
	s_mul_i32 s96, s84, 0x60000
	s_mov_b32 s97, 0
	s_sub_u32 s86, s24, 0x80000
	s_subb_u32 s87, s25, 0
	s_add_u32 s86, s86, s96
	s_addc_u32 s87, s87, 0
	v_mbcnt_hi_u32_b32 v233, -1, v0
	s_add_i32 s48, s39, 0xc000
	s_add_i32 s49, s39, 0xe000
	s_add_i32 s51, s50, 0x2000
	s_add_i32 s53, s52, 0x2000
	v_add_u32_e32 v234, s55, v3
	v_add_u32_e32 v235, s54, v3
	s_add_i32 s55, s55, s37
	s_mov_b32 s56, 0
	s_barrier
	s_lshr_b32 s100, s88, 2
	s_cmp_lg_u32 s100, 1
	s_cbranch_scc1 .Lpro_lag6
	s_barrier

.LBB0_1072:
.LBB0_1073:
	s_add_i32 s0, 0, 0x23f94
	s_waitcnt vmcnt(0)
	v_mov_b32_e32 v0, s0
	v_mbcnt_lo_u32_b32 v24, -1, 0
	v_mbcnt_hi_u32_b32 v24, -1, v24
	ds_read_b32 v0, v0
	s_waitcnt lgkmcnt(0)
	v_readfirstlane_b32 s4, v0
	s_ashr_i32 s40, s4, 3
	s_cmpk_gt_i32 s40, 0x7f
	s_cbranch_scc1 .LBB0_1091
	s_and_b32 s16, s4, 7
	s_and_b32 s0, s33, 0xffffffc0
	v_add_u32_e32 v25, s0, v24
	s_and_b32 s0, s40, 3
	s_lshl_b32 s1, s16, 2
	s_or_b32 s41, s1, s0
	s_movk_i32 s0, 0x100
	v_cmp_gt_i32_e64 s[2:3], s0, v25
	s_and_saveexec_b64 s[0:1], s[2:3]
	s_cbranch_execz .LBB0_1076
	v_lshl_add_u32 v0, s41, 8, v25
	v_ashrrev_i32_e32 v1, 31, v0
	v_lshlrev_b64 v[0:1], 8, v[0:1]
	v_lshl_add_u64 v[0:1], s[94:95], 0, v[0:1]
	s_mov_b64 s[8:9], 0x12000000
	v_lshl_add_u64 v[10:11], v[0:1], 0, s[8:9]
	v_add_co_u32_e32 v0, vcc, 0x12000000, v0
	global_load_dwordx4 v[248:251], v[10:11], off offset:32
	global_load_dwordx4 v[244:247], v[10:11], off offset:16
	global_load_dwordx4 v[240:243], v[10:11], off offset:96
	global_load_dwordx4 v[236:239], v[10:11], off offset:80
	v_addc_co_u32_e32 v1, vcc, 0, v1, vcc
	global_load_dwordx4 v[232:235], v[0:1], off
	global_load_dwordx4 v[228:231], v[10:11], off offset:64
	global_load_dwordx4 v[224:227], v[10:11], off offset:48
	global_load_dwordx4 v[220:223], v[10:11], off offset:112

.LBB0_1078:
	s_mov_b64 s[14:15], 0x80
	s_add_i32 m0, s46, 0x18000
	v_lshl_add_u64 v[22:23], v[22:23], 0, s[14:15]
	global_load_lds_dwordx4 v[22:23], off
	v_lshl_add_u64 v[20:21], v[20:21], 0, s[14:15]
	s_add_i32 m0, s46, 0x1a000
	s_add_i32 s50, s46, 0x8000
	s_add_i32 s51, s46, 0xa000
	global_load_lds_dwordx4 v[20:21], off
	v_lshl_add_u64 v[16:17], v[16:17], 0, s[14:15]
	s_mov_b32 m0, s50
	s_add_u32 s0, s10, 0x80080
	global_load_lds_dwordx4 v[16:17], off
	v_lshl_add_u64 v[16:17], v[18:19], 0, s[14:15]
	s_mov_b32 m0, s51
	s_addc_u32 s1, s11, 0
	global_load_lds_dwordx4 v[16:17], off
	s_add_i32 m0, s46, 0x1c000
	v_lshl_add_u64 v[16:17], s[0:1], 0, v[130:131]
	global_load_lds_dwordx4 v[16:17], off
	v_lshl_add_u64 v[16:17], s[0:1], 0, v[134:135]
	s_add_i32 m0, s46, 0x1e000
	s_nop 0
	global_load_lds_dwordx4 v[16:17], off
	s_waitcnt vmcnt(6)
	s_barrier
	s_and_saveexec_b64 s[0:1], s[2:3]
	s_cbranch_execz .LBB0_1080
	v_pk_add_f32 v[0:1], v[250:251], v[242:243]
	v_pk_add_f32 v[8:9], v[246:247], v[238:239]
	v_pk_add_f32 v[10:11], v[244:245], v[236:237]
	v_pk_add_f32 v[4:5], v[248:249], v[240:241]
	v_pk_add_f32 v[12:13], v[234:235], v[230:231]
	v_pk_add_f32 v[14:15], v[232:233], v[228:229]
	v_pk_add_f32 v[2:3], v[226:227], v[222:223]
	v_pk_add_f32 v[6:7], v[224:225], v[220:221]
	v_pk_add_f32 v[10:11], v[10:11], v[14:15]
	v_pk_add_f32 v[8:9], v[8:9], v[12:13]
	v_pk_add_f32 v[4:5], v[6:7], v[4:5]
	v_pk_add_f32 v[0:1], v[2:3], v[0:1]
	v_pk_add_f32 v[2:3], v[4:5], v[10:11]
	v_pk_add_f32 v[0:1], v[0:1], v[8:9]
	s_nop 0
	v_pk_mov_b32 v[4:5], v[2:3], v[0:1] op_sel:[1,0]
	v_mov_b32_e32 v3, v1
	v_pk_add_f32 v[0:1], v[4:5], v[2:3]
	s_nop 0
	v_add_f32_e32 v0, v0, v1
	v_mov_b32_e32 v1, 0x358637bd
	v_fmac_f32_e32 v1, 0x3a000000, v0
	v_rsq_f32_e32 v0, v1
	v_lshl_add_u32 v1, v25, 2, 0
	v_add_u32_e32 v1, 0x20000, v1
	ds_write_b32 v1, v0
.LBB0_1080:
	s_or_b64 exec, exec, s[0:1]
	s_mul_i32 s0, s16, 0x1400000
	s_add_u32 s0, s94, s0
	s_addc_u32 s1, s95, 0
	s_lshl_b32 s2, s16, 24
	s_sub_u32 s2, 0, s2
	s_subb_u32 s3, 0, 0
	s_add_u32 s0, s0, s2
	s_addc_u32 s1, s1, s3
	s_add_u32 s2, s0, 0x13000000
	s_addc_u32 s3, s1, 0
	v_ashrrev_i32_e32 v0, 6, v24
	s_lshl_b32 s0, s18, 13
	v_lshl_add_u32 v2, v0, 10, s0
	s_lshl_b32 s0, s88, 5
	s_and_b32 s54, s0, 0x60
	v_and_b32_e32 v148, 15, v24
	v_and_b32_e32 v1, 48, v24
	v_lshlrev_b32_e32 v3, 2, v24
	s_lshr_b32 s0, s54, 3
	v_lshl_or_b32 v1, v148, 6, v1
	v_and_b32_e32 v3, 32, v3
	v_add_lshl_u32 v0, v0, s0, 10
	v_bitop3_b32 v2, v1, v2, v3 bitop3:0xde
	v_bitop3_b32 v0, v1, v0, v3 bitop3:0xde
	v_lshlrev_b32_e32 v1, 15, v26
	v_and_b32_e32 v1, 0xffff0000, v1
	v_lshl_add_u32 v1, v27, 12, v1
	v_and_b32_e32 v3, 1, v26
	v_lshl_or_b32 v1, v3, 6, v1
	s_lshl_b32 s53, s18, 6
	v_lshl_add_u32 v136, v28, 1, v1
	v_lshlrev_b32_e32 v1, 15, v29
	s_cmpk_lt_u32 s33, 0x100
	v_and_b32_e32 v1, 0xffff0000, v1
	s_cselect_b64 s[16:17], -1, 0
	s_lshl_b32 s0, s18, 8
	v_lshl_add_u32 v1, v30, 12, v1
	v_and_b32_e32 v3, 1, v29
	s_add_i32 s55, s0, 0
	v_mov_b32_e32 v137, 0
	v_lshl_or_b32 v1, v3, 6, v1
	s_add_i32 s56, 0, 0x10000
	s_add_i32 s57, 0, 0x14000
	s_add_i32 s58, 0, 0x18000
	s_add_i32 s59, 0, 0x1c000
	s_mov_b32 s52, 0
	v_ashrrev_i32_e32 v149, 4, v24
	s_add_i32 s55, s55, 0x20000
	v_lshl_add_u32 v138, v31, 1, v1
	v_mov_b32_e32 v139, v137
	v_add_u32_e32 v150, s56, v0
	v_add_u32_e32 v151, s57, v0
	v_add_u32_e32 v152, 0, v2
	s_mov_b64 s[18:19], 0x80000
	v_add_u32_e32 v153, s58, v0
	v_add_u32_e32 v154, s59, v0
	s_mov_b64 s[20:21], 0x40000
	s_lshr_b32 s84, s88, 2
	s_mul_i32 s85, s84, 0x3000
	s_add_i32 s85, s85, s46
	s_mul_i32 s86, s84, 0x60000
	v_add_u32_e32 v222, s86, v128
	s_mov_b32 s60, 0x40000
	s_mov_b32 s61, 0x80000
	s_mov_b64 s[22:23], 0xc0000
	s_mov_b32 s62, 0xc0000
	s_mov_b64 s[24:25], 0x200000
	s_mov_b32 s63, 0x200000
	s_mov_b64 s[26:27], 0x240000
	s_mov_b32 s64, 0x240000
	s_mov_b64 s[28:29], 0x280000
	s_mov_b32 s65, 0x280000
	s_mov_b64 s[30:31], 0x2c0000
	s_mov_b32 s66, 0x2c0000
	s_lshr_b32 s100, s88, 2
	s_cmp_lg_u32 s100, 1
	s_cbranch_scc1 .Lpro_lag7
	s_barrier

.LBB0_1190:
	s_add_u32 s14, s94, 0xf200000
	s_addc_u32 s15, s95, 0
	s_add_u32 s16, s94, 0x12000000
	s_mov_b64 s[18:19], 0x80
	s_addc_u32 s17, s95, 0
	s_bfe_u32 s43, s33, 0x20006
	s_add_i32 m0, s39, 0x18000
	v_lshl_add_u64 v[6:7], v[6:7], 0, s[18:19]
	s_lshl_b32 s44, s3, 6
	s_lshl_b32 s45, s43, 5
	global_load_lds_dwordx4 v[6:7], off
	v_lshl_add_u64 v[4:5], v[4:5], 0, s[18:19]
	s_add_i32 m0, s39, 0x1a000
	s_add_i32 s46, s39, 0x8000
	s_add_i32 s47, s39, 0xa000
	global_load_lds_dwordx4 v[4:5], off
	v_lshl_add_u64 v[0:1], v[0:1], 0, s[18:19]
	s_mov_b32 m0, s46
	s_add_u32 s20, s8, 0x200080
	global_load_lds_dwordx4 v[0:1], off
	v_lshl_add_u64 v[0:1], v[2:3], 0, s[18:19]
	s_mov_b32 m0, s47
	s_addc_u32 s21, s9, 0
	global_load_lds_dwordx4 v[0:1], off
	s_add_i32 m0, s39, 0x1c000
	v_lshl_add_u64 v[0:1], s[20:21], 0, v[188:189]
	global_load_lds_dwordx4 v[0:1], off
	v_lshl_add_u64 v[0:1], s[20:21], 0, v[184:185]
	s_add_i32 m0, s39, 0x1e000
	v_and_b32_e32 v229, 15, v9
	global_load_lds_dwordx4 v[0:1], off
	v_and_b32_e32 v0, 48, v9
	v_and_b32_e32 v1, 0xfffffc00, v11
	v_lshlrev_b32_e32 v3, 2, v9
	s_cmpk_lt_u32 s33, 0x100
	v_lshl_add_u32 v2, s3, 13, v1
	v_lshl_or_b32 v0, v229, 6, v0
	v_and_b32_e32 v3, 32, v3
	v_lshl_add_u32 v1, s43, 12, v1
	s_cselect_b64 s[22:23], -1, 0
	s_lshl_b32 s0, s0, 22
	v_bitop3_b32 v2, v0, v2, v3 bitop3:0xde
	v_bitop3_b32 v3, v0, v1, v3 bitop3:0xde
	s_lshl_b32 s1, s1, 22
	v_lshlrev_b32_e32 v0, 17, v13
	s_or_b32 s0, s2, s0
	v_and_b32_e32 v0, 0xfffc0000, v0
	s_add_u32 s0, s94, s0
	v_lshl_add_u32 v0, v14, 14, v0
	v_and_b32_e32 v1, 1, v13
	s_addc_u32 s2, s95, 0
	v_lshl_or_b32 v0, v1, 6, v0
	s_add_u32 s0, s0, s1
	v_lshl_add_u32 v0, v15, 1, v0
	v_mov_b32_e32 v1, v189
	s_addc_u32 s1, s2, 0
	v_lshl_add_u64 v[192:193], s[0:1], 0, v[0:1]
	v_lshlrev_b32_e32 v0, 17, v8
	v_and_b32_e32 v0, 0xfffc0000, v0
	v_lshl_add_u32 v0, v10, 14, v0
	v_and_b32_e32 v1, 1, v8
	v_lshl_or_b32 v0, v1, 6, v0
	s_waitcnt vmcnt(6)
	v_lshl_add_u32 v0, v12, 1, v0
	v_mov_b32_e32 v1, v189
	s_add_i32 s50, 0, 0x10000
	s_add_i32 s52, 0, 0x14000
	v_lshl_add_u64 v[194:195], s[0:1], 0, v[0:1]
	v_add_u32_e32 v230, s50, v3
	v_add_u32_e32 v231, s52, v3
	v_mbcnt_lo_u32_b32 v0, -1, 0
	s_add_i32 s50, s50, s37
	s_add_i32 s52, s52, s37
	s_add_i32 s54, 0, 0x18000
	s_add_i32 s55, 0, 0x1c000
	v_ashrrev_i32_e32 v228, 4, v9
	s_mov_b32 s21, 0
	v_add_u32_e32 v232, 0, v2
	s_mov_b64 s[24:25], 0x131fff80
	v_mbcnt_hi_u32_b32 v233, -1, v0
	s_add_i32 s48, s39, 0xc000
	s_add_i32 s49, s39, 0xe000
	s_add_i32 s51, s50, 0x2000
	s_add_i32 s53, s52, 0x2000
	v_add_u32_e32 v234, s54, v3
	v_add_u32_e32 v235, s55, v3
	s_mov_b32 s56, 0
	s_lshr_b32 s84, s88, 2
	s_mul_i32 s85, s84, 0x3000
	s_add_i32 s85, s85, s39
	s_mul_i32 s96, s84, 0x180000
	s_mov_b32 s97, 0
	s_sub_u32 s86, s24, 0x200000
	s_subb_u32 s87, s25, 0
	s_add_u32 s86, s86, s96
	s_addc_u32 s87, s87, 0
	s_barrier
	s_lshr_b32 s100, s88, 2
	s_cmp_lg_u32 s100, 1
	s_cbranch_scc1 .Lpro_lag8
	s_barrier

.LBB0_1312:
.LBB0_1313:
	s_add_i32 s0, 0, 0x23f94
	s_waitcnt vmcnt(0)
	v_mov_b32_e32 v0, s0
	v_mbcnt_lo_u32_b32 v24, -1, 0
	v_mbcnt_hi_u32_b32 v24, -1, v24
	ds_read_b32 v0, v0
	s_waitcnt lgkmcnt(0)
	v_readfirstlane_b32 s4, v0
	s_ashr_i32 s38, s4, 3
	s_cmp_gt_i32 s38, 31
	s_cbranch_scc1 .LBB0_1331
	s_and_b32 s14, s4, 7
	s_and_b32 s0, s33, 0xffffffc0
	v_add_u32_e32 v25, s0, v24
	s_and_b32 s0, s38, 3
	s_lshl_b32 s1, s14, 2
	s_or_b32 s39, s1, s0
	s_movk_i32 s0, 0x100
	v_cmp_gt_i32_e64 s[2:3], s0, v25
	s_and_saveexec_b64 s[0:1], s[2:3]
	s_cbranch_execz .LBB0_1316
	v_lshl_add_u32 v0, s39, 8, v25
	v_ashrrev_i32_e32 v1, 31, v0
	v_lshlrev_b64 v[0:1], 8, v[0:1]
	v_lshl_add_u64 v[0:1], s[94:95], 0, v[0:1]
	s_mov_b64 s[6:7], 0x12000000
	v_lshl_add_u64 v[10:11], v[0:1], 0, s[6:7]
	v_add_co_u32_e32 v0, vcc, 0x12000000, v0
	global_load_dwordx4 v[248:251], v[10:11], off offset:32
	global_load_dwordx4 v[244:247], v[10:11], off offset:16
	global_load_dwordx4 v[240:243], v[10:11], off offset:96
	global_load_dwordx4 v[236:239], v[10:11], off offset:80
	v_addc_co_u32_e32 v1, vcc, 0, v1, vcc
	global_load_dwordx4 v[232:235], v[0:1], off
	global_load_dwordx4 v[228:231], v[10:11], off offset:64
	global_load_dwordx4 v[224:227], v[10:11], off offset:48
	global_load_dwordx4 v[220:223], v[10:11], off offset:112

.LBB0_1318:
	s_mov_b64 s[10:11], 0x80
	s_add_i32 m0, s44, 0x18000
	v_lshl_add_u64 v[22:23], v[22:23], 0, s[10:11]
	global_load_lds_dwordx4 v[22:23], off
	v_lshl_add_u64 v[20:21], v[20:21], 0, s[10:11]
	s_add_i32 m0, s44, 0x1a000
	s_add_i32 s48, s44, 0x8000
	s_add_i32 s49, s44, 0xa000
	global_load_lds_dwordx4 v[20:21], off
	v_lshl_add_u64 v[16:17], v[16:17], 0, s[10:11]
	s_mov_b32 m0, s48
	s_add_u32 s12, s0, 0x80080
	global_load_lds_dwordx4 v[16:17], off
	v_lshl_add_u64 v[16:17], v[18:19], 0, s[10:11]
	s_mov_b32 m0, s49
	s_addc_u32 s13, s1, 0
	global_load_lds_dwordx4 v[16:17], off
	s_add_i32 m0, s44, 0x1c000
	v_lshl_add_u64 v[16:17], s[12:13], 0, v[130:131]
	global_load_lds_dwordx4 v[16:17], off
	v_lshl_add_u64 v[16:17], s[12:13], 0, v[134:135]
	s_add_i32 m0, s44, 0x1e000
	s_nop 0
	global_load_lds_dwordx4 v[16:17], off
	s_waitcnt vmcnt(6)
	s_barrier
	s_and_saveexec_b64 s[12:13], s[2:3]
	s_cbranch_execz .LBB0_1320
	v_pk_add_f32 v[0:1], v[250:251], v[242:243]
	v_pk_add_f32 v[8:9], v[246:247], v[238:239]
	v_pk_add_f32 v[10:11], v[244:245], v[236:237]
	v_pk_add_f32 v[4:5], v[248:249], v[240:241]
	v_pk_add_f32 v[12:13], v[234:235], v[230:231]
	v_pk_add_f32 v[14:15], v[232:233], v[228:229]
	v_pk_add_f32 v[2:3], v[226:227], v[222:223]
	v_pk_add_f32 v[6:7], v[224:225], v[220:221]
	v_pk_add_f32 v[10:11], v[10:11], v[14:15]
	v_pk_add_f32 v[8:9], v[8:9], v[12:13]
	v_pk_add_f32 v[4:5], v[6:7], v[4:5]
	v_pk_add_f32 v[0:1], v[2:3], v[0:1]
	v_pk_add_f32 v[2:3], v[4:5], v[10:11]
	v_pk_add_f32 v[0:1], v[0:1], v[8:9]
	s_nop 0
	v_pk_mov_b32 v[4:5], v[2:3], v[0:1] op_sel:[1,0]
	v_mov_b32_e32 v3, v1
	v_pk_add_f32 v[0:1], v[4:5], v[2:3]
	s_nop 0
	v_add_f32_e32 v0, v0, v1
	v_mov_b32_e32 v1, 0x358637bd
	v_fmac_f32_e32 v1, 0x3a000000, v0
	v_rsq_f32_e32 v0, v1
	v_lshl_add_u32 v1, v25, 2, 0
	v_add_u32_e32 v1, 0x20000, v1
	ds_write_b32 v1, v0
.LBB0_1320:
	s_or_b64 exec, exec, s[12:13]
	s_mul_i32 s2, s14, 0x1400000
	s_add_u32 s2, s94, s2
	s_addc_u32 s3, s95, 0
	s_lshl_b32 s12, s14, 22
	s_sub_u32 s12, 0, s12
	s_subb_u32 s13, 0, 0
	s_add_u32 s2, s2, s12
	s_addc_u32 s3, s3, s13
	s_add_u32 s2, s2, 0x14000000
	s_addc_u32 s3, s3, 0
	v_ashrrev_i32_e32 v0, 6, v24
	s_lshl_b32 s12, s15, 13
	v_lshl_add_u32 v2, v0, 10, s12
	s_lshl_b32 s12, s88, 5
	s_and_b32 s52, s12, 0x60
	v_and_b32_e32 v146, 15, v24
	v_and_b32_e32 v1, 48, v24
	v_lshlrev_b32_e32 v3, 2, v24
	s_lshr_b32 s12, s52, 3
	v_lshl_or_b32 v1, v146, 6, v1
	v_and_b32_e32 v3, 32, v3
	v_add_lshl_u32 v0, v0, s12, 10
	v_bitop3_b32 v2, v1, v2, v3 bitop3:0xde
	v_bitop3_b32 v0, v1, v0, v3 bitop3:0xde
	v_lshlrev_b32_e32 v1, 15, v26
	v_and_b32_e32 v1, 0xffff0000, v1
	v_lshl_add_u32 v1, v27, 12, v1
	v_and_b32_e32 v3, 1, v26
	v_lshl_or_b32 v1, v3, 6, v1
	s_lshl_b32 s51, s15, 6
	v_lshl_add_u32 v136, v28, 1, v1
	v_lshlrev_b32_e32 v1, 15, v29
	s_cmpk_lt_u32 s33, 0x100
	v_and_b32_e32 v1, 0xffff0000, v1
	s_cselect_b64 s[12:13], -1, 0
	s_lshl_b32 s14, s15, 8
	v_lshl_add_u32 v1, v30, 12, v1
	v_and_b32_e32 v3, 1, v29
	s_add_i32 s54, s14, 0
	v_mov_b32_e32 v137, 0
	v_lshl_or_b32 v1, v3, 6, v1
	s_add_i32 s56, 0, 0x10000
	s_add_i32 s57, 0, 0x14000
	s_add_i32 s58, 0, 0x18000
	s_add_i32 s59, 0, 0x1c000
	s_mov_b32 s50, 0
	v_ashrrev_i32_e32 v147, 4, v24
	s_mov_b32 s53, 0x20000
	s_add_i32 s54, s54, 0x20000
	v_lshl_add_u32 v138, v31, 1, v1
	v_mov_b32_e32 v139, v137
	s_mov_b32 s55, 0x10000
	v_add_u32_e32 v148, s56, v0
	v_add_u32_e32 v149, s57, v0
	v_add_u32_e32 v150, 0, v2
	s_mov_b64 s[14:15], 0x80000
	v_add_u32_e32 v151, s58, v0
	v_add_u32_e32 v152, s59, v0
	s_mov_b64 s[16:17], 0x10000
	s_mov_b64 s[18:19], 0x20000
	s_mov_b64 s[20:21], 0x30000
	s_mov_b32 s60, 0x30000
	s_mov_b32 s61, 0x80000
	s_mov_b64 s[22:23], 0x90000
	s_mov_b32 s62, 0x90000
	s_mov_b64 s[24:25], 0xa0000
	s_mov_b32 s63, 0xa0000
	s_mov_b64 s[26:27], 0xb0000
	s_mov_b32 s64, 0xb0000
	s_lshr_b32 s84, s88, 2
	s_mul_i32 s85, s84, 0x3000
	s_add_i32 s85, s85, s44
	s_mul_i32 s86, s84, 0x60000
	v_add_u32_e32 v222, s86, v136
	s_lshr_b32 s100, s88, 2
	s_cmp_lg_u32 s100, 1
	s_cbranch_scc1 .Lpro_lag9
	s_barrier

.LBB0_1522:
	s_add_u32 s16, s94, 0xf200000
	s_addc_u32 s17, s95, 0
	s_add_u32 s18, s94, 0x12000000
	s_mov_b64 s[20:21], 0x80
	s_addc_u32 s19, s95, 0
	s_add_i32 m0, s7, 0x18000
	v_lshl_add_u64 v[6:7], v[6:7], 0, s[20:21]
	s_bfe_u32 s44, s33, 0x20006
	s_lshl_b32 s45, s2, 6
	global_load_lds_dwordx4 v[6:7], off
	v_lshl_add_u64 v[4:5], v[4:5], 0, s[20:21]
	s_add_i32 m0, s7, 0x1a000
	s_add_i32 s46, s7, 0x8000
	s_add_i32 s47, s7, 0xa000
	global_load_lds_dwordx4 v[4:5], off
	v_lshl_add_u64 v[0:1], v[0:1], 0, s[20:21]
	s_mov_b32 m0, s46
	s_add_u32 s0, s8, 0x80080
	global_load_lds_dwordx4 v[0:1], off
	v_lshl_add_u64 v[0:1], v[2:3], 0, s[20:21]
	s_mov_b32 m0, s47
	s_addc_u32 s1, s9, 0
	global_load_lds_dwordx4 v[0:1], off
	s_add_i32 m0, s7, 0x1c000
	v_lshl_add_u64 v[0:1], s[0:1], 0, v[146:147]
	global_load_lds_dwordx4 v[0:1], off
	v_lshl_add_u64 v[0:1], s[0:1], 0, v[144:145]
	s_add_i32 m0, s7, 0x1e000
	v_and_b32_e32 v182, 15, v8
	global_load_lds_dwordx4 v[0:1], off
	v_and_b32_e32 v0, 48, v8
	v_and_b32_e32 v1, 0xfffffc00, v12
	v_lshlrev_b32_e32 v3, 2, v8
	v_lshl_add_u32 v2, s2, 13, v1
	v_lshl_or_b32 v0, v182, 6, v0
	v_and_b32_e32 v3, 32, v3
	v_lshl_add_u32 v1, s44, 12, v1
	v_bitop3_b32 v2, v0, v2, v3 bitop3:0xde
	v_bitop3_b32 v184, v0, v1, v3 bitop3:0xde
	v_lshlrev_b32_e32 v0, 15, v13
	v_and_b32_e32 v0, 0xffff0000, v0
	v_lshl_add_u32 v0, v14, 12, v0
	v_and_b32_e32 v1, 1, v13
	v_lshl_or_b32 v0, v1, 6, v0
	v_lshl_add_u32 v148, v15, 1, v0
	v_lshlrev_b32_e32 v0, 15, v9
	s_cmpk_lt_u32 s33, 0x100
	v_and_b32_e32 v0, 0xffff0000, v0
	s_cselect_b64 s[24:25], -1, 0
	s_lshl_b32 s48, s44, 4
	v_lshl_add_u32 v0, v10, 12, v0
	v_and_b32_e32 v1, 1, v9
	s_waitcnt vmcnt(6)
	s_waitcnt lgkmcnt(0)
	s_add_u32 s26, s12, 0x2000
	v_lshl_or_b32 v0, v1, 6, v0
	s_addc_u32 s27, s13, 0
	v_lshl_add_u32 v150, v11, 1, v0
	s_add_i32 s49, 0, 0x10000
	s_add_i32 s50, 0, 0x14000
	v_mbcnt_lo_u32_b32 v0, -1, 0
	v_ashrrev_i32_e32 v183, 4, v8
	s_mov_b32 s23, 0
	v_mov_b32_e32 v149, v147
	v_mov_b32_e32 v151, v147
	v_add_u32_e32 v185, s49, v184
	v_add_u32_e32 v186, s50, v184
	v_add_u32_e32 v187, 0, v2
	v_mbcnt_hi_u32_b32 v188, -1, v0
	s_mov_b32 s51, 0
	s_barrier
	s_lshr_b32 s84, s88, 2
	s_mul_i32 s85, s84, 0x3000
	s_add_i32 s85, s85, s7
	s_mul_i32 s86, s84, 0x60000
	v_add_u32_e32 v222, s86, v148
	s_lshr_b32 s100, s88, 2
	s_cmp_lg_u32 s100, 1
	s_cbranch_scc1 .Lpro_lag10
	s_barrier

.LBB0_1644:
.LBB0_1645:
	s_add_i32 s0, 0, 0x23f94
	s_waitcnt vmcnt(0)
	v_mov_b32_e32 v0, s0
	v_mbcnt_lo_u32_b32 v24, -1, 0
	v_mbcnt_hi_u32_b32 v24, -1, v24
	ds_read_b32 v0, v0
	s_waitcnt lgkmcnt(0)
	v_readfirstlane_b32 s4, v0
	s_ashr_i32 s19, s4, 3
	s_cmp_gt_i32 s19, 31
	s_cbranch_scc1 .LBB0_1663
	s_and_b32 s16, s4, 7
	s_and_b32 s0, s33, 0xffffffc0
	v_add_u32_e32 v25, s0, v24
	s_and_b32 s0, s19, 3
	s_lshl_b32 s1, s16, 2
	s_or_b32 s42, s1, s0
	s_movk_i32 s0, 0x100
	v_cmp_gt_i32_e64 s[2:3], s0, v25
	s_and_saveexec_b64 s[0:1], s[2:3]
	s_cbranch_execz .LBB0_1648
	v_lshl_add_u32 v0, s42, 8, v25
	v_ashrrev_i32_e32 v1, 31, v0
	v_lshlrev_b64 v[0:1], 8, v[0:1]
	v_lshl_add_u64 v[50:51], s[94:95], 0, v[0:1]
	s_mov_b64 s[8:9], 0x12000000
	v_lshl_add_u64 v[66:67], v[50:51], 0, s[8:9]
	v_add_co_u32_e32 v68, vcc, 0x12000000, v50
	global_load_dwordx4 v[248:251], v[66:67], off offset:48
	global_load_dwordx4 v[244:247], v[66:67], off offset:32
	global_load_dwordx4 v[240:243], v[66:67], off offset:16
	global_load_dwordx4 v[236:239], v[66:67], off offset:96
	global_load_dwordx4 v[232:235], v[66:67], off offset:80
	global_load_dwordx4 v[228:231], v[66:67], off offset:160
	global_load_dwordx4 v[224:227], v[66:67], off offset:144
	global_load_dwordx4 v[220:223], v[66:67], off offset:112
	global_load_dwordx4 v[216:219], v[66:67], off offset:128
	global_load_dwordx4 v[212:215], v[66:67], off offset:192
	global_load_dwordx4 v[208:211], v[66:67], off offset:224
	global_load_dwordx4 v[204:207], v[66:67], off offset:208
	v_addc_co_u32_e32 v69, vcc, 0, v51, vcc
	global_load_dwordx4 v[200:203], v[68:69], off
	global_load_dwordx4 v[196:199], v[66:67], off offset:64
	global_load_dwordx4 v[192:195], v[66:67], off offset:176
	global_load_dwordx4 v[188:191], v[66:67], off offset:240

.LBB0_1650:
	s_mov_b64 s[12:13], 0x80
	s_add_i32 m0, s47, 0x18000
	v_lshl_add_u64 v[22:23], v[22:23], 0, s[12:13]
	global_load_lds_dwordx4 v[22:23], off
	v_lshl_add_u64 v[20:21], v[20:21], 0, s[12:13]
	s_add_i32 m0, s47, 0x1a000
	s_add_i32 s51, s47, 0x8000
	s_add_i32 s52, s47, 0xa000
	global_load_lds_dwordx4 v[20:21], off
	v_lshl_add_u64 v[16:17], v[16:17], 0, s[12:13]
	s_mov_b32 m0, s51
	s_add_u32 s14, s10, 0x80080
	global_load_lds_dwordx4 v[16:17], off
	v_lshl_add_u64 v[16:17], v[18:19], 0, s[12:13]
	s_mov_b32 m0, s52
	s_addc_u32 s15, s11, 0
	global_load_lds_dwordx4 v[16:17], off
	s_add_i32 m0, s47, 0x1c000
	v_lshl_add_u64 v[16:17], s[14:15], 0, v[130:131]
	global_load_lds_dwordx4 v[16:17], off
	v_lshl_add_u64 v[16:17], s[14:15], 0, v[134:135]
	s_add_i32 m0, s47, 0x1e000
	s_nop 0
	global_load_lds_dwordx4 v[16:17], off
	s_waitcnt vmcnt(6)
	s_barrier
	s_and_saveexec_b64 s[14:15], s[2:3]
	s_cbranch_execz .LBB0_1652
	v_pk_add_f32 v[6:7], v[246:247], v[238:239]
	v_pk_add_f32 v[10:11], v[242:243], v[234:235]
	v_pk_add_f32 v[184:185], v[240:241], v[232:233]
	v_pk_add_f32 v[4:5], v[244:245], v[236:237]
	v_pk_add_f32 v[186:187], v[250:251], v[222:223]
	v_pk_add_f32 v[180:181], v[248:249], v[220:221]
	v_pk_add_f32 v[12:13], v[218:219], v[214:215]
	v_pk_add_f32 v[182:183], v[230:231], v[210:211]
	v_pk_add_f32 v[0:1], v[226:227], v[206:207]
	v_pk_add_f32 v[2:3], v[224:225], v[204:205]
	v_pk_add_f32 v[176:177], v[228:229], v[208:209]
	v_pk_add_f32 v[14:15], v[216:217], v[212:213]
	v_pk_add_f32 v[178:179], v[202:203], v[198:199]
	v_pk_add_f32 v[172:173], v[200:201], v[196:197]
	v_pk_add_f32 v[8:9], v[10:11], v[0:1]
	v_pk_add_f32 v[10:11], v[184:185], v[2:3]
	v_pk_add_f32 v[0:1], v[6:7], v[182:183]
	v_pk_add_f32 v[2:3], v[4:5], v[176:177]
	v_pk_add_f32 v[4:5], v[194:195], v[190:191]
	v_pk_add_f32 v[6:7], v[192:193], v[188:189]
	v_pk_add_f32 v[12:13], v[178:179], v[12:13]
	v_pk_add_f32 v[14:15], v[172:173], v[14:15]
	v_pk_add_f32 v[4:5], v[186:187], v[4:5]
	v_pk_add_f32 v[6:7], v[180:181], v[6:7]
	v_pk_add_f32 v[10:11], v[10:11], v[14:15]
	v_pk_add_f32 v[8:9], v[8:9], v[12:13]
	v_pk_add_f32 v[2:3], v[6:7], v[2:3]
	v_pk_add_f32 v[0:1], v[4:5], v[0:1]
	v_pk_add_f32 v[2:3], v[2:3], v[10:11]
	v_pk_add_f32 v[0:1], v[0:1], v[8:9]
	s_nop 0
	v_pk_mov_b32 v[4:5], v[2:3], v[0:1] op_sel:[1,0]
	v_mov_b32_e32 v3, v1
	v_pk_add_f32 v[0:1], v[4:5], v[2:3]
	s_nop 0
	v_add_f32_e32 v0, v0, v1
	v_mov_b32_e32 v1, 0x358637bd
	v_fmac_f32_e32 v1, 0x3a000000, v0
	v_rsq_f32_e32 v0, v1
	v_lshl_add_u32 v1, v25, 2, 0
	v_add_u32_e32 v1, 0x20000, v1
	ds_write_b32 v1, v0

.LBB0_1943:
.LBB0_1944:
	s_add_i32 s0, 0, 0x23f94
	s_waitcnt vmcnt(0)
	v_mov_b32_e32 v0, s0
	v_mbcnt_lo_u32_b32 v24, -1, 0
	v_mbcnt_hi_u32_b32 v24, -1, v24
	ds_read_b32 v0, v0
	s_waitcnt lgkmcnt(0)
	v_readfirstlane_b32 s6, v0
	s_ashr_i32 s40, s6, 3
	s_cmpk_gt_i32 s40, 0x7f
	s_cbranch_scc1 .LBB0_1962
	s_and_b32 s16, s6, 7
	s_and_b32 s0, s33, 0xffffffc0
	v_add_u32_e32 v25, s0, v24
	s_and_b32 s0, s40, 3
	s_lshl_b32 s1, s16, 2
	s_or_b32 s41, s1, s0
	s_movk_i32 s0, 0x100
	v_cmp_gt_i32_e64 s[2:3], s0, v25
	s_and_saveexec_b64 s[0:1], s[2:3]
	s_cbranch_execz .LBB0_1947
	v_lshl_add_u32 v0, s41, 8, v25
	v_ashrrev_i32_e32 v1, 31, v0
	v_lshlrev_b64 v[0:1], 8, v[0:1]
	v_lshl_add_u64 v[0:1], s[94:95], 0, v[0:1]
	s_mov_b64 s[8:9], 0x12000000
	v_lshl_add_u64 v[10:11], v[0:1], 0, s[8:9]
	v_add_co_u32_e32 v0, vcc, 0x12000000, v0
	global_load_dwordx4 v[248:251], v[10:11], off offset:32
	global_load_dwordx4 v[244:247], v[10:11], off offset:16
	global_load_dwordx4 v[240:243], v[10:11], off offset:96
	global_load_dwordx4 v[236:239], v[10:11], off offset:80
	v_addc_co_u32_e32 v1, vcc, 0, v1, vcc
	global_load_dwordx4 v[232:235], v[0:1], off
	global_load_dwordx4 v[228:231], v[10:11], off offset:64
	global_load_dwordx4 v[224:227], v[10:11], off offset:48
	global_load_dwordx4 v[220:223], v[10:11], off offset:112

.LBB0_2061:
	s_mov_b64 s[8:9], 0x80
	s_add_i32 m0, s1, 0x18000
	v_lshl_add_u64 v[6:7], v[6:7], 0, s[8:9]
	s_bfe_u32 s29, s33, 0x20006
	s_lshl_b32 s42, s10, 6
	global_load_lds_dwordx4 v[6:7], off
	v_lshl_add_u64 v[4:5], v[4:5], 0, s[8:9]
	s_add_i32 m0, s1, 0x1a000
	s_add_i32 s43, s1, 0x8000
	s_add_i32 s44, s1, 0xa000
	global_load_lds_dwordx4 v[4:5], off
	v_lshl_add_u64 v[0:1], v[0:1], 0, s[8:9]
	s_mov_b32 m0, s43
	s_add_u32 s14, s12, 0x200080
	global_load_lds_dwordx4 v[0:1], off
	v_lshl_add_u64 v[0:1], v[2:3], 0, s[8:9]
	s_mov_b32 m0, s44
	s_addc_u32 s15, s13, 0
	global_load_lds_dwordx4 v[0:1], off
	s_add_i32 m0, s1, 0x1c000
	v_lshl_add_u64 v[0:1], s[14:15], 0, v[132:133]
	global_load_lds_dwordx4 v[0:1], off
	v_lshl_add_u64 v[0:1], s[14:15], 0, v[128:129]
	s_add_i32 m0, s1, 0x1e000
	v_and_b32_e32 v144, 15, v201
	global_load_lds_dwordx4 v[0:1], off
	v_and_b32_e32 v0, 48, v201
	v_and_b32_e32 v1, 0xfffffc00, v10
	v_lshlrev_b32_e32 v3, 2, v201
	v_lshl_add_u32 v2, s10, 13, v1
	v_lshl_or_b32 v0, v144, 6, v0
	v_and_b32_e32 v3, 32, v3
	v_lshl_add_u32 v1, s29, 12, v1
	v_bitop3_b32 v4, v0, v2, v3 bitop3:0xde
	v_bitop3_b32 v145, v0, v1, v3 bitop3:0xde
	v_lshlrev_b32_e32 v0, 17, v12
	v_and_b32_e32 v0, 0xfffc0000, v0
	v_lshl_add_u32 v0, v13, 14, v0
	v_and_b32_e32 v1, 1, v12
	v_lshl_or_b32 v0, v1, 6, v0
	s_mov_b64 s[14:15], 0x200080
	v_lshl_add_u32 v0, v14, 1, v0
	v_mov_b32_e32 v1, v133
	v_lshl_add_u64 v[136:137], v[0:1], 0, s[14:15]
	v_lshlrev_b32_e32 v0, 17, v8
	v_and_b32_e32 v0, 0xfffc0000, v0
	v_lshl_add_u32 v0, v9, 14, v0
	v_and_b32_e32 v1, 1, v8
	s_cmpk_lt_u32 s33, 0x100
	v_lshl_or_b32 v0, v1, 6, v0
	s_waitcnt vmcnt(6)
	s_cselect_b64 s[10:11], -1, 0
	v_lshl_add_u32 v0, v11, 1, v0
	v_mov_b32_e32 v1, v133
	v_mov_b32_e32 v2, v133
	v_mov_b32_e32 v3, v133
	s_add_i32 s33, 0, 0x10000
	s_add_i32 s45, 0, 0x14000
	v_lshl_add_u64 v[138:139], v[0:1], 0, s[14:15]
	v_mov_b32_e32 v0, v133
	v_add_u32_e32 v146, 0, v4
	s_add_i32 s48, s33, s38
	s_add_i32 s50, s45, s38
	v_mov_b64_e32 v[6:7], v[2:3]
	v_mov_b64_e32 v[18:19], v[2:3]
	v_mov_b64_e32 v[22:23], v[2:3]
	v_mov_b64_e32 v[34:35], v[2:3]
	v_mov_b64_e32 v[38:39], v[2:3]
	v_mov_b64_e32 v[50:51], v[2:3]
	v_mov_b64_e32 v[54:55], v[2:3]
	v_mov_b64_e32 v[10:11], v[2:3]
	v_mov_b64_e32 v[14:15], v[2:3]
	v_mov_b64_e32 v[26:27], v[2:3]
	v_mov_b64_e32 v[30:31], v[2:3]
	v_mov_b64_e32 v[42:43], v[2:3]
	v_mov_b64_e32 v[46:47], v[2:3]
	v_mov_b64_e32 v[58:59], v[2:3]
	v_mov_b64_e32 v[62:63], v[2:3]
	v_mov_b64_e32 v[66:67], v[2:3]
	v_mov_b64_e32 v[70:71], v[2:3]
	v_mov_b64_e32 v[82:83], v[2:3]
	v_mov_b64_e32 v[86:87], v[2:3]
	v_mov_b64_e32 v[98:99], v[2:3]
	v_mov_b64_e32 v[102:103], v[2:3]
	v_mov_b64_e32 v[114:115], v[2:3]
	v_mov_b64_e32 v[118:119], v[2:3]
	v_mov_b64_e32 v[74:75], v[2:3]
	v_mov_b64_e32 v[78:79], v[2:3]
	v_mov_b64_e32 v[90:91], v[2:3]
	v_mov_b64_e32 v[94:95], v[2:3]
	v_mov_b64_e32 v[106:107], v[2:3]
	v_mov_b64_e32 v[110:111], v[2:3]
	v_mov_b64_e32 v[122:123], v[2:3]
	v_mov_b64_e32 v[126:127], v[2:3]
	s_mov_b32 s55, 0
	s_add_i32 s46, s1, 0xc000
	s_add_i32 s47, s1, 0xe000
	s_add_i32 s49, s48, 0x2000
	s_add_i32 s51, s50, 0x2000
	s_add_i32 s52, 0, 0x18000
	v_mov_b64_e32 v[4:5], v[0:1]
	v_mov_b64_e32 v[16:17], v[0:1]
	v_mov_b64_e32 v[20:21], v[0:1]
	v_mov_b64_e32 v[32:33], v[0:1]
	v_mov_b64_e32 v[36:37], v[0:1]
	v_mov_b64_e32 v[48:49], v[0:1]
	v_mov_b64_e32 v[52:53], v[0:1]
	v_mov_b64_e32 v[8:9], v[0:1]
	v_mov_b64_e32 v[12:13], v[0:1]
	v_mov_b64_e32 v[24:25], v[0:1]
	v_mov_b64_e32 v[28:29], v[0:1]
	v_mov_b64_e32 v[40:41], v[0:1]
	v_mov_b64_e32 v[44:45], v[0:1]
	v_mov_b64_e32 v[56:57], v[0:1]
	v_mov_b64_e32 v[60:61], v[0:1]
	v_mov_b64_e32 v[64:65], v[0:1]
	v_mov_b64_e32 v[68:69], v[0:1]
	v_mov_b64_e32 v[80:81], v[0:1]
	v_mov_b64_e32 v[84:85], v[0:1]
	v_mov_b64_e32 v[96:97], v[0:1]
	v_mov_b64_e32 v[100:101], v[0:1]
	v_mov_b64_e32 v[112:113], v[0:1]
	v_mov_b64_e32 v[116:117], v[0:1]
	v_mov_b64_e32 v[72:73], v[0:1]
	v_mov_b64_e32 v[76:77], v[0:1]
	v_mov_b64_e32 v[88:89], v[0:1]
	v_mov_b64_e32 v[92:93], v[0:1]
	v_mov_b64_e32 v[104:105], v[0:1]
	v_mov_b64_e32 v[108:109], v[0:1]
	v_mov_b64_e32 v[120:121], v[0:1]
	v_mov_b64_e32 v[124:125], v[0:1]
	s_barrier
	s_lshr_b32 s100, s88, 2
	s_cmp_lg_u32 s100, 1
	s_cbranch_scc1 .Lpro_lag14
	s_barrier
.Lpro_lag14:
.LBB0_2062:
	s_mov_b64 s[22:23], s[12:13]
	s_add_u32 s56, s22, 0x100
	s_addc_u32 s57, s23, 0
	s_add_i32 s54, s55, 1
	s_lshl_b32 s12, s54, 5
	s_add_i32 s12, s12, s30
	s_cmp_lt_i32 s12, 32
	s_cselect_b64 s[20:21], -1, 0
	s_cmp_gt_i32 s12, 31
	s_mov_b32 s16, s53
	s_cselect_b64 s[14:15], -1, 0
	s_ashr_i32 s53, s12, 2
	s_and_b64 s[12:13], s[20:21], exec
	s_cselect_b32 s12, s53, s16
	s_cselect_b32 s16, s34, s34
	s_ashr_i32 s17, s16, 31
	s_lshl_b64 s[16:17], s[16:17], 22
	s_add_u32 s16, s31, s16
	s_addc_u32 s17, s35, s17
	s_and_b64 s[24:25], s[20:21], exec
	s_cselect_b32 s58, s17, s19
	s_cselect_b32 s59, s16, s18
	s_ashr_i32 s13, s12, 31
	s_lshl_b64 s[12:13], s[12:13], 22
	s_add_u32 s12, s36, s12
	s_addc_u32 s13, s37, s13
	s_and_b64 s[24:25], s[20:21], exec
	s_cselect_b32 s60, s13, s23
	s_cselect_b32 s61, s12, s22
	v_lshl_add_u64 v[140:141], s[18:19], 0, v[136:137]
	v_lshl_add_u64 v[142:143], s[18:19], 0, v[138:139]
	s_lshr_b32 s84, s88, 2
	s_mul_i32 s85, s84, 0x3000
	s_add_i32 s85, s85, s1
	s_mul_i32 s96, s84, 0x180000
	s_mov_b32 s97, 0
	s_sub_u32 s86, s96, 0x200000
	s_subb_u32 s87, 0, 0
	s_mov_b32 s62, -2
	s_mov_b64 s[22:23], 0
